# K-loop LDS-DMA loads use saddr form (no 64-bit VALU address adds in load segments)
# speedup vs baseline: 1.0064x; 1.0064x over previous
.LBB0_268:
	v_add_u32_e32 v160, s43, v1
	ds_read_b128 v[156:159], v160
	ds_read_b128 v[162:165], v160 offset:1024
	ds_read_b128 v[166:169], v160 offset:2048
	ds_read_b128 v[170:173], v160 offset:3072
	v_add_u32_e32 v160, s44, v1
	ds_read_b128 v[174:177], v160
	ds_read_b128 v[178:181], v160 offset:1024
	ds_read_b128 v[182:185], v160 offset:2048
	ds_read_b128 v[192:195], v160 offset:3072
	s_add_u32 s52, s30, 0x10000
	s_addc_u32 s53, s31, 0
	s_cmp_eq_u32 s67, 12
	s_cselect_b32 s64, s51, s52
	s_cselect_b32 s65, s50, s53
	s_cselect_b32 s62, s55, s61
	s_cselect_b32 s63, s54, s66
	s_add_u32 s56, s64, 0x8000
	s_addc_u32 s57, s65, 0
	s_add_i32 m0, s36, 0xc000
	ds_read_b128 v[200:203], v155
	ds_read_b128 v[204:207], v155 offset:1024
	ds_read_b128 v[208:211], v155 offset:2048
	ds_read_b128 v[212:215], v155 offset:3072
	ds_read_b128 v[216:219], v155 offset:4096
	ds_read_b128 v[220:223], v155 offset:5120
	ds_read_b128 v[224:227], v155 offset:6144
	ds_read_b128 v[228:231], v155 offset:7168
	global_load_lds_dwordx4 v146, s[30:31] sc1
	s_add_i32 m0, s36, 0xe000
	s_nop 0
	global_load_lds_dwordx4 v148, s[30:31] sc1
	s_waitcnt vmcnt(8)
	s_waitcnt lgkmcnt(0)
	s_barrier
	s_setprio 1
	s_waitcnt lgkmcnt(0)
	v_mfma_f32_16x16x32_bf16 v[118:121], v[156:159], v[200:203], v[118:121]
	v_mfma_f32_16x16x32_bf16 v[110:113], v[166:169], v[200:203], v[110:113]
	v_mfma_f32_16x16x32_bf16 v[102:105], v[156:159], v[208:211], v[102:105]
	v_mfma_f32_16x16x32_bf16 v[94:97], v[166:169], v[208:211], v[94:97]
	v_mfma_f32_16x16x32_bf16 v[86:89], v[156:159], v[216:219], v[86:89]
	v_mfma_f32_16x16x32_bf16 v[78:81], v[166:169], v[216:219], v[78:81]
	v_mfma_f32_16x16x32_bf16 v[62:65], v[156:159], v[224:227], v[62:65]
	v_mfma_f32_16x16x32_bf16 v[54:57], v[166:169], v[224:227], v[54:57]
	v_mfma_f32_16x16x32_bf16 v[118:121], v[162:165], v[204:207], v[118:121]
	v_mfma_f32_16x16x32_bf16 v[110:113], v[170:173], v[204:207], v[110:113]
	v_mfma_f32_16x16x32_bf16 v[102:105], v[162:165], v[212:215], v[102:105]
	v_mfma_f32_16x16x32_bf16 v[94:97], v[170:173], v[212:215], v[94:97]
	v_mfma_f32_16x16x32_bf16 v[86:89], v[162:165], v[220:223], v[86:89]
	v_mfma_f32_16x16x32_bf16 v[78:81], v[170:173], v[220:223], v[78:81]
	v_mfma_f32_16x16x32_bf16 v[62:65], v[162:165], v[228:231], v[62:65]
	v_mfma_f32_16x16x32_bf16 v[54:57], v[170:173], v[228:231], v[54:57]
	s_setprio 0
	s_setprio 1
	v_mfma_f32_16x16x32_bf16 v[126:129], v[174:177], v[200:203], v[126:129]
	v_mfma_f32_16x16x32_bf16 v[122:125], v[182:185], v[200:203], v[122:125]
	v_mfma_f32_16x16x32_bf16 v[114:117], v[174:177], v[208:211], v[114:117]
	v_mfma_f32_16x16x32_bf16 v[106:109], v[182:185], v[208:211], v[106:109]
	v_mfma_f32_16x16x32_bf16 v[98:101], v[174:177], v[216:219], v[98:101]
	v_mfma_f32_16x16x32_bf16 v[90:93], v[182:185], v[216:219], v[90:93]
	v_mfma_f32_16x16x32_bf16 v[82:85], v[174:177], v[224:227], v[82:85]
	v_mfma_f32_16x16x32_bf16 v[70:73], v[182:185], v[224:227], v[70:73]
	v_mfma_f32_16x16x32_bf16 v[126:129], v[178:181], v[204:207], v[126:129]
	v_mfma_f32_16x16x32_bf16 v[122:125], v[192:195], v[204:207], v[122:125]
	v_mfma_f32_16x16x32_bf16 v[114:117], v[178:181], v[212:215], v[114:117]
	v_mfma_f32_16x16x32_bf16 v[106:109], v[192:195], v[212:215], v[106:109]
	v_mfma_f32_16x16x32_bf16 v[98:101], v[178:181], v[220:223], v[98:101]
	v_mfma_f32_16x16x32_bf16 v[90:93], v[192:195], v[220:223], v[90:93]
	v_mfma_f32_16x16x32_bf16 v[82:85], v[178:181], v[228:231], v[82:85]
	v_mfma_f32_16x16x32_bf16 v[70:73], v[192:195], v[228:231], v[70:73]
	s_setprio 0
	s_barrier
	s_add_i32 s30, s43, s5
	s_mov_b32 m0, s30
	ds_read_b128 v[200:203], v155 offset:16384
	ds_read_b128 v[204:207], v155 offset:17408
	ds_read_b128 v[208:211], v155 offset:18432
	ds_read_b128 v[212:215], v155 offset:19456
	ds_read_b128 v[216:219], v155 offset:20480
	ds_read_b128 v[220:223], v155 offset:21504
	ds_read_b128 v[224:227], v155 offset:22528
	ds_read_b128 v[228:231], v155 offset:23552
	global_load_lds_dwordx4 v134, s[62:63] sc1
	s_add_i32 m0, s30, 0x2000
	s_add_u32 s30, s62, 0x4000
	s_addc_u32 s31, s63, 0
	s_add_i32 s69, s44, s5
	global_load_lds_dwordx4 v136, s[62:63] sc1
	s_mov_b32 m0, s69
	s_nop 0
	global_load_lds_dwordx4 v134, s[30:31] sc1
	s_add_i32 m0, s69, 0x2000
	s_nop 0
	global_load_lds_dwordx4 v136, s[30:31] sc1
	s_mov_b32 m0, s36
	s_nop 0
	global_load_lds_dwordx4 v132, s[64:65] sc1
	s_mov_b32 m0, s37
	s_nop 0
	global_load_lds_dwordx4 v130, s[64:65] sc1
	s_waitcnt vmcnt(8)
	s_waitcnt lgkmcnt(0)
	s_barrier
	s_setprio 1
	s_waitcnt lgkmcnt(0)
	v_mfma_f32_16x16x32_bf16 v[58:61], v[156:159], v[200:203], v[58:61]
	v_mfma_f32_16x16x32_bf16 v[46:49], v[166:169], v[200:203], v[46:49]
	v_mfma_f32_16x16x32_bf16 v[38:41], v[156:159], v[208:211], v[38:41]
	v_mfma_f32_16x16x32_bf16 v[30:33], v[166:169], v[208:211], v[30:33]
	v_mfma_f32_16x16x32_bf16 v[22:25], v[156:159], v[216:219], v[22:25]
	v_mfma_f32_16x16x32_bf16 v[14:17], v[166:169], v[216:219], v[14:17]
	v_mfma_f32_16x16x32_bf16 v[6:9], v[156:159], v[224:227], v[6:9]
	v_mfma_f32_16x16x32_bf16 v[2:5], v[166:169], v[224:227], v[2:5]
	v_mfma_f32_16x16x32_bf16 v[58:61], v[162:165], v[204:207], v[58:61]
	v_mfma_f32_16x16x32_bf16 v[46:49], v[170:173], v[204:207], v[46:49]
	v_mfma_f32_16x16x32_bf16 v[38:41], v[162:165], v[212:215], v[38:41]
	v_mfma_f32_16x16x32_bf16 v[30:33], v[170:173], v[212:215], v[30:33]
	v_mfma_f32_16x16x32_bf16 v[22:25], v[162:165], v[220:223], v[22:25]
	v_mfma_f32_16x16x32_bf16 v[14:17], v[170:173], v[220:223], v[14:17]
	v_mfma_f32_16x16x32_bf16 v[6:9], v[162:165], v[228:231], v[6:9]
	v_mfma_f32_16x16x32_bf16 v[2:5], v[170:173], v[228:231], v[2:5]
	s_setprio 0
	s_setprio 1
	v_mfma_f32_16x16x32_bf16 v[74:77], v[174:177], v[200:203], v[74:77]
	v_mfma_f32_16x16x32_bf16 v[66:69], v[182:185], v[200:203], v[66:69]
	v_mfma_f32_16x16x32_bf16 v[50:53], v[174:177], v[208:211], v[50:53]
	v_mfma_f32_16x16x32_bf16 v[42:45], v[182:185], v[208:211], v[42:45]
	v_mfma_f32_16x16x32_bf16 v[34:37], v[174:177], v[216:219], v[34:37]
	v_mfma_f32_16x16x32_bf16 v[26:29], v[182:185], v[216:219], v[26:29]
	v_mfma_f32_16x16x32_bf16 v[18:21], v[174:177], v[224:227], v[18:21]
	v_mfma_f32_16x16x32_bf16 v[10:13], v[182:185], v[224:227], v[10:13]
	v_mfma_f32_16x16x32_bf16 v[74:77], v[178:181], v[204:207], v[74:77]
	v_mfma_f32_16x16x32_bf16 v[66:69], v[192:195], v[204:207], v[66:69]
	v_mfma_f32_16x16x32_bf16 v[50:53], v[178:181], v[212:215], v[50:53]
	v_mfma_f32_16x16x32_bf16 v[42:45], v[192:195], v[212:215], v[42:45]
	v_mfma_f32_16x16x32_bf16 v[34:37], v[178:181], v[220:223], v[34:37]
	v_mfma_f32_16x16x32_bf16 v[26:29], v[192:195], v[220:223], v[26:29]
	v_mfma_f32_16x16x32_bf16 v[18:21], v[178:181], v[228:231], v[18:21]
	v_mfma_f32_16x16x32_bf16 v[10:13], v[192:195], v[228:231], v[10:13]
	s_setprio 0
	s_barrier
	v_add_u32_e32 v160, s45, v1
	ds_read_b128 v[156:159], v160
	ds_read_b128 v[162:165], v160 offset:1024
	ds_read_b128 v[166:169], v160 offset:2048
	ds_read_b128 v[170:173], v160 offset:3072
	v_add_u32_e32 v160, s46, v1
	ds_read_b128 v[174:177], v160
	ds_read_b128 v[178:181], v160 offset:1024
	ds_read_b128 v[182:185], v160 offset:2048
	ds_read_b128 v[192:195], v160 offset:3072
	s_add_u32 s30, s64, 0x4000
	s_addc_u32 s31, s65, 0
	s_mov_b32 m0, s38
	ds_read_b128 v[200:203], v155 offset:32768
	ds_read_b128 v[204:207], v155 offset:33792
	ds_read_b128 v[208:211], v155 offset:34816
	ds_read_b128 v[212:215], v155 offset:35840
	ds_read_b128 v[216:219], v155 offset:36864
	ds_read_b128 v[220:223], v155 offset:37888
	ds_read_b128 v[224:227], v155 offset:38912
	ds_read_b128 v[228:231], v155 offset:39936
	global_load_lds_dwordx4 v132, s[30:31] sc1
	s_mov_b32 m0, s39
	s_nop 0
	global_load_lds_dwordx4 v130, s[30:31] sc1
	s_waitcnt vmcnt(8)
	s_waitcnt lgkmcnt(0)
	s_barrier
	s_setprio 1
	s_waitcnt lgkmcnt(0)
	v_mfma_f32_16x16x32_bf16 v[118:121], v[156:159], v[200:203], v[118:121]
	v_mfma_f32_16x16x32_bf16 v[110:113], v[166:169], v[200:203], v[110:113]
	v_mfma_f32_16x16x32_bf16 v[102:105], v[156:159], v[208:211], v[102:105]
	v_mfma_f32_16x16x32_bf16 v[94:97], v[166:169], v[208:211], v[94:97]
	v_mfma_f32_16x16x32_bf16 v[86:89], v[156:159], v[216:219], v[86:89]
	v_mfma_f32_16x16x32_bf16 v[78:81], v[166:169], v[216:219], v[78:81]
	v_mfma_f32_16x16x32_bf16 v[62:65], v[156:159], v[224:227], v[62:65]
	v_mfma_f32_16x16x32_bf16 v[54:57], v[166:169], v[224:227], v[54:57]
	v_mfma_f32_16x16x32_bf16 v[118:121], v[162:165], v[204:207], v[118:121]
	v_mfma_f32_16x16x32_bf16 v[110:113], v[170:173], v[204:207], v[110:113]
	v_mfma_f32_16x16x32_bf16 v[102:105], v[162:165], v[212:215], v[102:105]
	v_mfma_f32_16x16x32_bf16 v[94:97], v[170:173], v[212:215], v[94:97]
	v_mfma_f32_16x16x32_bf16 v[86:89], v[162:165], v[220:223], v[86:89]
	v_mfma_f32_16x16x32_bf16 v[78:81], v[170:173], v[220:223], v[78:81]
	v_mfma_f32_16x16x32_bf16 v[62:65], v[162:165], v[228:231], v[62:65]
	v_mfma_f32_16x16x32_bf16 v[54:57], v[170:173], v[228:231], v[54:57]
	s_setprio 0
	s_setprio 1
	v_mfma_f32_16x16x32_bf16 v[126:129], v[174:177], v[200:203], v[126:129]
	v_mfma_f32_16x16x32_bf16 v[122:125], v[182:185], v[200:203], v[122:125]
	v_mfma_f32_16x16x32_bf16 v[114:117], v[174:177], v[208:211], v[114:117]
	v_mfma_f32_16x16x32_bf16 v[106:109], v[182:185], v[208:211], v[106:109]
	v_mfma_f32_16x16x32_bf16 v[98:101], v[174:177], v[216:219], v[98:101]
	v_mfma_f32_16x16x32_bf16 v[90:93], v[182:185], v[216:219], v[90:93]
	v_mfma_f32_16x16x32_bf16 v[82:85], v[174:177], v[224:227], v[82:85]
	v_mfma_f32_16x16x32_bf16 v[70:73], v[182:185], v[224:227], v[70:73]
	v_mfma_f32_16x16x32_bf16 v[126:129], v[178:181], v[204:207], v[126:129]
	v_mfma_f32_16x16x32_bf16 v[122:125], v[192:195], v[204:207], v[122:125]
	v_mfma_f32_16x16x32_bf16 v[114:117], v[178:181], v[212:215], v[114:117]
	v_mfma_f32_16x16x32_bf16 v[106:109], v[192:195], v[212:215], v[106:109]
	v_mfma_f32_16x16x32_bf16 v[98:101], v[178:181], v[220:223], v[98:101]
	v_mfma_f32_16x16x32_bf16 v[90:93], v[192:195], v[220:223], v[90:93]
	v_mfma_f32_16x16x32_bf16 v[82:85], v[178:181], v[228:231], v[82:85]
	v_mfma_f32_16x16x32_bf16 v[70:73], v[192:195], v[228:231], v[70:73]
	s_setprio 0
	s_barrier
	s_add_u32 s30, s62, 0x8000
	s_addc_u32 s31, s63, 0
	s_add_i32 s64, s45, s5
	s_mov_b32 m0, s64
	ds_read_b128 v[200:203], v155 offset:49152
	ds_read_b128 v[204:207], v155 offset:50176
	ds_read_b128 v[208:211], v155 offset:51200
	ds_read_b128 v[212:215], v155 offset:52224
	ds_read_b128 v[216:219], v155 offset:53248
	ds_read_b128 v[220:223], v155 offset:54272
	ds_read_b128 v[224:227], v155 offset:55296
	ds_read_b128 v[228:231], v155 offset:56320
	global_load_lds_dwordx4 v134, s[30:31] sc1
	s_add_i32 m0, s64, 0x2000
	s_nop 0
	global_load_lds_dwordx4 v136, s[30:31] sc1
	s_add_u32 s30, s62, 0xc000
	s_addc_u32 s31, s63, 0
	s_add_i32 s62, s46, s5
	s_mov_b32 m0, s62
	s_nop 0
	global_load_lds_dwordx4 v134, s[30:31] sc1
	s_add_i32 m0, s62, 0x2000
	s_nop 0
	global_load_lds_dwordx4 v136, s[30:31] sc1
	s_mov_b32 m0, s40
	s_nop 0
	global_load_lds_dwordx4 v132, s[56:57] sc1
	s_mov_b32 m0, s41
	s_nop 0
	global_load_lds_dwordx4 v130, s[56:57] sc1
	s_waitcnt vmcnt(8)
	s_waitcnt lgkmcnt(0)
	s_barrier
	s_setprio 1
	s_waitcnt lgkmcnt(0)
	v_mfma_f32_16x16x32_bf16 v[58:61], v[156:159], v[200:203], v[58:61]
	v_mfma_f32_16x16x32_bf16 v[46:49], v[166:169], v[200:203], v[46:49]
	v_mfma_f32_16x16x32_bf16 v[38:41], v[156:159], v[208:211], v[38:41]
	v_mfma_f32_16x16x32_bf16 v[30:33], v[166:169], v[208:211], v[30:33]
	v_mfma_f32_16x16x32_bf16 v[22:25], v[156:159], v[216:219], v[22:25]
	v_mfma_f32_16x16x32_bf16 v[14:17], v[166:169], v[216:219], v[14:17]
	v_mfma_f32_16x16x32_bf16 v[6:9], v[156:159], v[224:227], v[6:9]
	v_mfma_f32_16x16x32_bf16 v[2:5], v[166:169], v[224:227], v[2:5]
	v_mfma_f32_16x16x32_bf16 v[58:61], v[162:165], v[204:207], v[58:61]
	v_mfma_f32_16x16x32_bf16 v[46:49], v[170:173], v[204:207], v[46:49]
	v_mfma_f32_16x16x32_bf16 v[38:41], v[162:165], v[212:215], v[38:41]
	v_mfma_f32_16x16x32_bf16 v[30:33], v[170:173], v[212:215], v[30:33]
	v_mfma_f32_16x16x32_bf16 v[22:25], v[162:165], v[220:223], v[22:25]
	v_mfma_f32_16x16x32_bf16 v[14:17], v[170:173], v[220:223], v[14:17]
	v_mfma_f32_16x16x32_bf16 v[6:9], v[162:165], v[228:231], v[6:9]
	v_mfma_f32_16x16x32_bf16 v[2:5], v[170:173], v[228:231], v[2:5]
	s_setprio 0
	s_setprio 1
	v_mfma_f32_16x16x32_bf16 v[74:77], v[174:177], v[200:203], v[74:77]
	v_mfma_f32_16x16x32_bf16 v[66:69], v[182:185], v[200:203], v[66:69]
	v_mfma_f32_16x16x32_bf16 v[50:53], v[174:177], v[208:211], v[50:53]
	v_mfma_f32_16x16x32_bf16 v[42:45], v[182:185], v[208:211], v[42:45]
	v_mfma_f32_16x16x32_bf16 v[34:37], v[174:177], v[216:219], v[34:37]
	v_mfma_f32_16x16x32_bf16 v[26:29], v[182:185], v[216:219], v[26:29]
	v_mfma_f32_16x16x32_bf16 v[18:21], v[174:177], v[224:227], v[18:21]
	v_mfma_f32_16x16x32_bf16 v[10:13], v[182:185], v[224:227], v[10:13]
	v_mfma_f32_16x16x32_bf16 v[74:77], v[178:181], v[204:207], v[74:77]
	v_mfma_f32_16x16x32_bf16 v[66:69], v[192:195], v[204:207], v[66:69]
	v_mfma_f32_16x16x32_bf16 v[50:53], v[178:181], v[212:215], v[50:53]
	v_mfma_f32_16x16x32_bf16 v[42:45], v[192:195], v[212:215], v[42:45]
	v_mfma_f32_16x16x32_bf16 v[34:37], v[178:181], v[220:223], v[34:37]
	v_mfma_f32_16x16x32_bf16 v[26:29], v[192:195], v[220:223], v[26:29]
	v_mfma_f32_16x16x32_bf16 v[18:21], v[178:181], v[228:231], v[18:21]
	v_mfma_f32_16x16x32_bf16 v[10:13], v[192:195], v[228:231], v[10:13]
	s_setprio 0
	s_barrier
	s_add_i32 s67, s67, 2
	s_add_u32 s61, s61, 0x10000
	s_addc_u32 s66, s66, 0
	s_cmp_gt_u32 s67, 13
	s_mov_b64 s[30:31], s[52:53]
	s_cbranch_scc0 .LBB0_268
	s_and_b64 vcc, exec, s[10:11]
	s_cbranch_vccz .LBB0_271
	s_barrier

.LBB0_404:
	s_add_u32 s29, s30, s8
	v_add_u32_e32 v157, s45, v153
	s_addc_u32 s55, s31, s9
	ds_read_b128 v[162:165], v157
	ds_read_b128 v[166:169], v157 offset:1024
	ds_read_b128 v[170:173], v157 offset:2048
	ds_read_b128 v[174:177], v157 offset:3072
	v_add_u32_e32 v157, s47, v153
	s_add_u32 s29, s29, 0x10000
	ds_read_b128 v[178:181], v157
	ds_read_b128 v[182:185], v157 offset:1024
	ds_read_b128 v[192:195], v157 offset:2048
	ds_read_b128 v[200:203], v157 offset:3072
	s_addc_u32 s55, s55, 0
	s_add_u32 s62, s61, s8
	s_addc_u32 s63, s69, s9
	s_cmp_eq_u32 s8, 0x150000
	s_cselect_b32 s66, s71, s29
	s_cselect_b32 s67, s70, s55
	s_cselect_b32 s64, s79, s62
	s_cselect_b32 s65, s78, s63
	s_add_u32 s62, s66, 0x8000
	s_addc_u32 s63, s67, 0
	s_add_i32 s29, s37, 0xc000
	v_lshl_add_u64 v[158:159], v[146:147], 0, s[8:9]
	s_mov_b32 m0, s29
	s_add_i32 s55, s37, 0xe000
	ds_read_b128 v[204:207], v155
	ds_read_b128 v[208:211], v155 offset:1024
	ds_read_b128 v[212:215], v155 offset:2048
	ds_read_b128 v[216:219], v155 offset:3072
	ds_read_b128 v[220:223], v155 offset:4096
	ds_read_b128 v[224:227], v155 offset:5120
	ds_read_b128 v[228:231], v155 offset:6144
	ds_read_b128 v[232:235], v155 offset:7168
	global_load_lds_dwordx4 v[158:159], off sc1
	v_lshl_add_u64 v[158:159], v[148:149], 0, s[8:9]
	s_mov_b32 m0, s55
	s_nop 0
	global_load_lds_dwordx4 v[158:159], off sc1
	s_waitcnt vmcnt(8)
	s_waitcnt lgkmcnt(0)
	s_barrier
	s_setprio 1
	s_waitcnt lgkmcnt(0)
	v_mfma_f32_16x16x32_bf16 v[114:117], v[162:165], v[204:207], v[114:117]
	v_mfma_f32_16x16x32_bf16 v[118:121], v[170:173], v[204:207], v[118:121]
	v_mfma_f32_16x16x32_bf16 v[98:101], v[162:165], v[212:215], v[98:101]
	v_mfma_f32_16x16x32_bf16 v[102:105], v[170:173], v[212:215], v[102:105]
	v_mfma_f32_16x16x32_bf16 v[82:85], v[162:165], v[220:223], v[82:85]
	v_mfma_f32_16x16x32_bf16 v[86:89], v[170:173], v[220:223], v[86:89]
	v_mfma_f32_16x16x32_bf16 v[66:69], v[162:165], v[228:231], v[66:69]
	v_mfma_f32_16x16x32_bf16 v[70:73], v[170:173], v[228:231], v[70:73]
	v_mfma_f32_16x16x32_bf16 v[114:117], v[166:169], v[208:211], v[114:117]
	v_mfma_f32_16x16x32_bf16 v[118:121], v[174:177], v[208:211], v[118:121]
	v_mfma_f32_16x16x32_bf16 v[98:101], v[166:169], v[216:219], v[98:101]
	v_mfma_f32_16x16x32_bf16 v[102:105], v[174:177], v[216:219], v[102:105]
	v_mfma_f32_16x16x32_bf16 v[82:85], v[166:169], v[224:227], v[82:85]
	v_mfma_f32_16x16x32_bf16 v[86:89], v[174:177], v[224:227], v[86:89]
	v_mfma_f32_16x16x32_bf16 v[66:69], v[166:169], v[232:235], v[66:69]
	v_mfma_f32_16x16x32_bf16 v[70:73], v[174:177], v[232:235], v[70:73]
	s_setprio 0
	s_setprio 1
	v_mfma_f32_16x16x32_bf16 v[122:125], v[178:181], v[204:207], v[122:125]
	v_mfma_f32_16x16x32_bf16 v[126:129], v[192:195], v[204:207], v[126:129]
	v_mfma_f32_16x16x32_bf16 v[106:109], v[178:181], v[212:215], v[106:109]
	v_mfma_f32_16x16x32_bf16 v[110:113], v[192:195], v[212:215], v[110:113]
	v_mfma_f32_16x16x32_bf16 v[90:93], v[178:181], v[220:223], v[90:93]
	v_mfma_f32_16x16x32_bf16 v[94:97], v[192:195], v[220:223], v[94:97]
	v_mfma_f32_16x16x32_bf16 v[74:77], v[178:181], v[228:231], v[74:77]
	v_mfma_f32_16x16x32_bf16 v[78:81], v[192:195], v[228:231], v[78:81]
	v_mfma_f32_16x16x32_bf16 v[122:125], v[182:185], v[208:211], v[122:125]
	v_mfma_f32_16x16x32_bf16 v[126:129], v[200:203], v[208:211], v[126:129]
	v_mfma_f32_16x16x32_bf16 v[106:109], v[182:185], v[216:219], v[106:109]
	v_mfma_f32_16x16x32_bf16 v[110:113], v[200:203], v[216:219], v[110:113]
	v_mfma_f32_16x16x32_bf16 v[90:93], v[182:185], v[224:227], v[90:93]
	v_mfma_f32_16x16x32_bf16 v[94:97], v[200:203], v[224:227], v[94:97]
	v_mfma_f32_16x16x32_bf16 v[74:77], v[182:185], v[232:235], v[74:77]
	v_mfma_f32_16x16x32_bf16 v[78:81], v[200:203], v[232:235], v[78:81]
	s_setprio 0
	s_barrier
	s_add_i32 s81, s45, s35
	s_mov_b32 m0, s81
	ds_read_b128 v[204:207], v155 offset:16384
	ds_read_b128 v[208:211], v155 offset:17408
	ds_read_b128 v[212:215], v155 offset:18432
	ds_read_b128 v[216:219], v155 offset:19456
	ds_read_b128 v[220:223], v155 offset:20480
	ds_read_b128 v[224:227], v155 offset:21504
	ds_read_b128 v[228:231], v155 offset:22528
	ds_read_b128 v[232:235], v155 offset:23552
	global_load_lds_dwordx4 v132, s[64:65] sc1
	s_add_i32 m0, s81, 0x2000
	s_add_u32 s82, s64, 0x4000
	s_addc_u32 s83, s65, 0
	s_add_i32 s81, s47, s35
	global_load_lds_dwordx4 v136, s[64:65] sc1
	s_mov_b32 m0, s81
	s_nop 0
	global_load_lds_dwordx4 v132, s[82:83] sc1
	s_add_i32 m0, s81, 0x2000
	s_nop 0
	global_load_lds_dwordx4 v136, s[82:83] sc1
	s_mov_b32 m0, s37
	s_nop 0
	global_load_lds_dwordx4 v130, s[66:67] sc1
	s_mov_b32 m0, s39
	s_nop 0
	global_load_lds_dwordx4 v134, s[66:67] sc1
	s_waitcnt vmcnt(8)
	s_waitcnt lgkmcnt(0)
	s_barrier
	s_setprio 1
	s_waitcnt lgkmcnt(0)
	v_mfma_f32_16x16x32_bf16 v[50:53], v[162:165], v[204:207], v[50:53]
	v_mfma_f32_16x16x32_bf16 v[54:57], v[170:173], v[204:207], v[54:57]
	v_mfma_f32_16x16x32_bf16 v[34:37], v[162:165], v[212:215], v[34:37]
	v_mfma_f32_16x16x32_bf16 v[38:41], v[170:173], v[212:215], v[38:41]
	v_mfma_f32_16x16x32_bf16 v[18:21], v[162:165], v[220:223], v[18:21]
	v_mfma_f32_16x16x32_bf16 v[22:25], v[170:173], v[220:223], v[22:25]
	v_mfma_f32_16x16x32_bf16 v[2:5], v[162:165], v[228:231], v[2:5]
	v_mfma_f32_16x16x32_bf16 v[6:9], v[170:173], v[228:231], v[6:9]
	v_mfma_f32_16x16x32_bf16 v[50:53], v[166:169], v[208:211], v[50:53]
	v_mfma_f32_16x16x32_bf16 v[54:57], v[174:177], v[208:211], v[54:57]
	v_mfma_f32_16x16x32_bf16 v[34:37], v[166:169], v[216:219], v[34:37]
	v_mfma_f32_16x16x32_bf16 v[38:41], v[174:177], v[216:219], v[38:41]
	v_mfma_f32_16x16x32_bf16 v[18:21], v[166:169], v[224:227], v[18:21]
	v_mfma_f32_16x16x32_bf16 v[22:25], v[174:177], v[224:227], v[22:25]
	v_mfma_f32_16x16x32_bf16 v[2:5], v[166:169], v[232:235], v[2:5]
	v_mfma_f32_16x16x32_bf16 v[6:9], v[174:177], v[232:235], v[6:9]
	s_setprio 0
	s_setprio 1
	v_mfma_f32_16x16x32_bf16 v[58:61], v[178:181], v[204:207], v[58:61]
	v_mfma_f32_16x16x32_bf16 v[62:65], v[192:195], v[204:207], v[62:65]
	v_mfma_f32_16x16x32_bf16 v[42:45], v[178:181], v[212:215], v[42:45]
	v_mfma_f32_16x16x32_bf16 v[46:49], v[192:195], v[212:215], v[46:49]
	v_mfma_f32_16x16x32_bf16 v[26:29], v[178:181], v[220:223], v[26:29]
	v_mfma_f32_16x16x32_bf16 v[30:33], v[192:195], v[220:223], v[30:33]
	v_mfma_f32_16x16x32_bf16 v[10:13], v[178:181], v[228:231], v[10:13]
	v_mfma_f32_16x16x32_bf16 v[14:17], v[192:195], v[228:231], v[14:17]
	v_mfma_f32_16x16x32_bf16 v[58:61], v[182:185], v[208:211], v[58:61]
	v_mfma_f32_16x16x32_bf16 v[62:65], v[200:203], v[208:211], v[62:65]
	v_mfma_f32_16x16x32_bf16 v[42:45], v[182:185], v[216:219], v[42:45]
	v_mfma_f32_16x16x32_bf16 v[46:49], v[200:203], v[216:219], v[46:49]
	v_mfma_f32_16x16x32_bf16 v[26:29], v[182:185], v[224:227], v[26:29]
	v_mfma_f32_16x16x32_bf16 v[30:33], v[200:203], v[224:227], v[30:33]
	v_mfma_f32_16x16x32_bf16 v[10:13], v[182:185], v[232:235], v[10:13]
	v_mfma_f32_16x16x32_bf16 v[14:17], v[200:203], v[232:235], v[14:17]
	s_setprio 0
	s_barrier
	v_add_u32_e32 v157, s48, v153
	ds_read_b128 v[162:165], v157
	ds_read_b128 v[166:169], v157 offset:1024
	ds_read_b128 v[170:173], v157 offset:2048
	ds_read_b128 v[174:177], v157 offset:3072
	v_add_u32_e32 v157, s49, v153
	ds_read_b128 v[178:181], v157
	ds_read_b128 v[182:185], v157 offset:1024
	ds_read_b128 v[192:195], v157 offset:2048
	ds_read_b128 v[200:203], v157 offset:3072
	s_add_u32 s66, s66, 0x4000
	s_addc_u32 s67, s67, 0
	s_mov_b32 m0, s40
	ds_read_b128 v[204:207], v155 offset:32768
	ds_read_b128 v[208:211], v155 offset:33792
	ds_read_b128 v[212:215], v155 offset:34816
	ds_read_b128 v[216:219], v155 offset:35840
	ds_read_b128 v[220:223], v155 offset:36864
	ds_read_b128 v[224:227], v155 offset:37888
	ds_read_b128 v[228:231], v155 offset:38912
	ds_read_b128 v[232:235], v155 offset:39936
	global_load_lds_dwordx4 v130, s[66:67] sc1
	s_mov_b32 m0, s41
	s_nop 0
	global_load_lds_dwordx4 v134, s[66:67] sc1
	s_waitcnt vmcnt(8)
	s_waitcnt lgkmcnt(0)
	s_barrier
	s_setprio 1
	s_waitcnt lgkmcnt(0)
	v_mfma_f32_16x16x32_bf16 v[114:117], v[162:165], v[204:207], v[114:117]
	v_mfma_f32_16x16x32_bf16 v[118:121], v[170:173], v[204:207], v[118:121]
	v_mfma_f32_16x16x32_bf16 v[98:101], v[162:165], v[212:215], v[98:101]
	v_mfma_f32_16x16x32_bf16 v[102:105], v[170:173], v[212:215], v[102:105]
	v_mfma_f32_16x16x32_bf16 v[82:85], v[162:165], v[220:223], v[82:85]
	v_mfma_f32_16x16x32_bf16 v[86:89], v[170:173], v[220:223], v[86:89]
	v_mfma_f32_16x16x32_bf16 v[66:69], v[162:165], v[228:231], v[66:69]
	v_mfma_f32_16x16x32_bf16 v[70:73], v[170:173], v[228:231], v[70:73]
	v_mfma_f32_16x16x32_bf16 v[114:117], v[166:169], v[208:211], v[114:117]
	v_mfma_f32_16x16x32_bf16 v[118:121], v[174:177], v[208:211], v[118:121]
	v_mfma_f32_16x16x32_bf16 v[98:101], v[166:169], v[216:219], v[98:101]
	v_mfma_f32_16x16x32_bf16 v[102:105], v[174:177], v[216:219], v[102:105]
	v_mfma_f32_16x16x32_bf16 v[82:85], v[166:169], v[224:227], v[82:85]
	v_mfma_f32_16x16x32_bf16 v[86:89], v[174:177], v[224:227], v[86:89]
	v_mfma_f32_16x16x32_bf16 v[66:69], v[166:169], v[232:235], v[66:69]
	v_mfma_f32_16x16x32_bf16 v[70:73], v[174:177], v[232:235], v[70:73]
	s_setprio 0
	s_setprio 1
	v_mfma_f32_16x16x32_bf16 v[122:125], v[178:181], v[204:207], v[122:125]
	v_mfma_f32_16x16x32_bf16 v[126:129], v[192:195], v[204:207], v[126:129]
	v_mfma_f32_16x16x32_bf16 v[106:109], v[178:181], v[212:215], v[106:109]
	v_mfma_f32_16x16x32_bf16 v[110:113], v[192:195], v[212:215], v[110:113]
	v_mfma_f32_16x16x32_bf16 v[90:93], v[178:181], v[220:223], v[90:93]
	v_mfma_f32_16x16x32_bf16 v[94:97], v[192:195], v[220:223], v[94:97]
	v_mfma_f32_16x16x32_bf16 v[74:77], v[178:181], v[228:231], v[74:77]
	v_mfma_f32_16x16x32_bf16 v[78:81], v[192:195], v[228:231], v[78:81]
	v_mfma_f32_16x16x32_bf16 v[122:125], v[182:185], v[208:211], v[122:125]
	v_mfma_f32_16x16x32_bf16 v[126:129], v[200:203], v[208:211], v[126:129]
	v_mfma_f32_16x16x32_bf16 v[106:109], v[182:185], v[216:219], v[106:109]
	v_mfma_f32_16x16x32_bf16 v[110:113], v[200:203], v[216:219], v[110:113]
	v_mfma_f32_16x16x32_bf16 v[90:93], v[182:185], v[224:227], v[90:93]
	v_mfma_f32_16x16x32_bf16 v[94:97], v[200:203], v[224:227], v[94:97]
	v_mfma_f32_16x16x32_bf16 v[74:77], v[182:185], v[232:235], v[74:77]
	v_mfma_f32_16x16x32_bf16 v[78:81], v[200:203], v[232:235], v[78:81]
	s_setprio 0
	s_barrier
	s_add_u32 s66, s64, 0x8000
	s_addc_u32 s67, s65, 0
	s_add_i32 s81, s48, s35
	s_mov_b32 m0, s81
	ds_read_b128 v[204:207], v155 offset:49152
	ds_read_b128 v[208:211], v155 offset:50176
	ds_read_b128 v[212:215], v155 offset:51200
	ds_read_b128 v[216:219], v155 offset:52224
	ds_read_b128 v[220:223], v155 offset:53248
	ds_read_b128 v[224:227], v155 offset:54272
	ds_read_b128 v[228:231], v155 offset:55296
	ds_read_b128 v[232:235], v155 offset:56320
	global_load_lds_dwordx4 v132, s[66:67] sc1
	s_add_i32 m0, s81, 0x2000
	s_add_u32 s64, s64, 0xc000
	global_load_lds_dwordx4 v136, s[66:67] sc1
	s_addc_u32 s65, s65, 0
	s_add_i32 s66, s49, s35
	s_mov_b32 m0, s66
	s_nop 0
	global_load_lds_dwordx4 v132, s[64:65] sc1
	s_add_i32 m0, s66, 0x2000
	s_nop 0
	global_load_lds_dwordx4 v136, s[64:65] sc1
	s_mov_b32 m0, s43
	s_nop 0
	global_load_lds_dwordx4 v130, s[62:63] sc1
	s_mov_b32 m0, s44
	s_nop 0
	global_load_lds_dwordx4 v134, s[62:63] sc1
	s_waitcnt vmcnt(8)
	s_waitcnt lgkmcnt(0)
	s_barrier
	s_setprio 1
	s_waitcnt lgkmcnt(0)
	v_mfma_f32_16x16x32_bf16 v[50:53], v[162:165], v[204:207], v[50:53]
	v_mfma_f32_16x16x32_bf16 v[54:57], v[170:173], v[204:207], v[54:57]
	v_mfma_f32_16x16x32_bf16 v[34:37], v[162:165], v[212:215], v[34:37]
	v_mfma_f32_16x16x32_bf16 v[38:41], v[170:173], v[212:215], v[38:41]
	v_mfma_f32_16x16x32_bf16 v[18:21], v[162:165], v[220:223], v[18:21]
	v_mfma_f32_16x16x32_bf16 v[22:25], v[170:173], v[220:223], v[22:25]
	v_mfma_f32_16x16x32_bf16 v[2:5], v[162:165], v[228:231], v[2:5]
	v_mfma_f32_16x16x32_bf16 v[6:9], v[170:173], v[228:231], v[6:9]
	v_mfma_f32_16x16x32_bf16 v[50:53], v[166:169], v[208:211], v[50:53]
	v_mfma_f32_16x16x32_bf16 v[54:57], v[174:177], v[208:211], v[54:57]
	v_mfma_f32_16x16x32_bf16 v[34:37], v[166:169], v[216:219], v[34:37]
	v_mfma_f32_16x16x32_bf16 v[38:41], v[174:177], v[216:219], v[38:41]
	v_mfma_f32_16x16x32_bf16 v[18:21], v[166:169], v[224:227], v[18:21]
	v_mfma_f32_16x16x32_bf16 v[22:25], v[174:177], v[224:227], v[22:25]
	v_mfma_f32_16x16x32_bf16 v[2:5], v[166:169], v[232:235], v[2:5]
	v_mfma_f32_16x16x32_bf16 v[6:9], v[174:177], v[232:235], v[6:9]
	s_setprio 0
	s_setprio 1
	v_mfma_f32_16x16x32_bf16 v[58:61], v[178:181], v[204:207], v[58:61]
	v_mfma_f32_16x16x32_bf16 v[62:65], v[192:195], v[204:207], v[62:65]
	v_mfma_f32_16x16x32_bf16 v[42:45], v[178:181], v[212:215], v[42:45]
	v_mfma_f32_16x16x32_bf16 v[46:49], v[192:195], v[212:215], v[46:49]
	v_mfma_f32_16x16x32_bf16 v[26:29], v[178:181], v[220:223], v[26:29]
	v_mfma_f32_16x16x32_bf16 v[30:33], v[192:195], v[220:223], v[30:33]
	v_mfma_f32_16x16x32_bf16 v[10:13], v[178:181], v[228:231], v[10:13]
	v_mfma_f32_16x16x32_bf16 v[14:17], v[192:195], v[228:231], v[14:17]
	v_mfma_f32_16x16x32_bf16 v[58:61], v[182:185], v[208:211], v[58:61]
	v_mfma_f32_16x16x32_bf16 v[62:65], v[200:203], v[208:211], v[62:65]
	v_mfma_f32_16x16x32_bf16 v[42:45], v[182:185], v[216:219], v[42:45]
	v_mfma_f32_16x16x32_bf16 v[46:49], v[200:203], v[216:219], v[46:49]
	v_mfma_f32_16x16x32_bf16 v[26:29], v[182:185], v[224:227], v[26:29]
	v_mfma_f32_16x16x32_bf16 v[30:33], v[200:203], v[224:227], v[30:33]
	v_mfma_f32_16x16x32_bf16 v[10:13], v[182:185], v[232:235], v[10:13]
	v_mfma_f32_16x16x32_bf16 v[14:17], v[200:203], v[232:235], v[14:17]
	s_setprio 0
	s_barrier
	s_add_i32 s80, s80, 2
	s_add_u32 s8, s8, 0x10000
	s_addc_u32 s9, s9, 0
	s_cmp_gt_u32 s80, 41
	s_cbranch_scc0 .LBB0_404
	s_add_u32 s8, s61, 0xffff0000
	s_addc_u32 s9, s69, -1
	s_and_b64 vcc, exec, s[6:7]
	s_cbranch_vccnz .LBB0_391
	s_mov_b32 s10, s50
	s_mov_b32 s28, s51
	s_mov_b64 s[30:31], s[56:57]
	s_mov_b32 s46, s54
	v_mov_b64 v[114:115], 0
	v_mov_b64 v[116:117], 0
	v_mov_b64 v[118:119], 0
	v_mov_b64 v[120:121], 0
	v_mov_b64 v[98:99], 0
	v_mov_b64 v[100:101], 0
	v_mov_b64 v[102:103], 0
	v_mov_b64 v[104:105], 0
	v_mov_b64 v[82:83], 0
	v_mov_b64 v[84:85], 0
	v_mov_b64 v[86:87], 0
	v_mov_b64 v[88:89], 0
	v_mov_b64 v[66:67], 0
	v_mov_b64 v[68:69], 0
	v_mov_b64 v[70:71], 0
	v_mov_b64 v[72:73], 0
	v_mov_b64 v[122:123], 0
	v_mov_b64 v[124:125], 0
	v_mov_b64 v[126:127], 0
	v_mov_b64 v[128:129], 0
	v_mov_b64 v[106:107], 0
	v_mov_b64 v[108:109], 0
	v_mov_b64 v[110:111], 0
	v_mov_b64 v[112:113], 0
	v_mov_b64 v[90:91], 0
	v_mov_b64 v[92:93], 0
	v_mov_b64 v[94:95], 0
	v_mov_b64 v[96:97], 0
	v_mov_b64 v[74:75], 0
	v_mov_b64 v[76:77], 0
	v_mov_b64 v[78:79], 0
	v_mov_b64 v[80:81], 0
	v_mov_b64 v[50:51], 0
	v_mov_b64 v[52:53], 0
	v_mov_b64 v[54:55], 0
	v_mov_b64 v[56:57], 0
	v_mov_b64 v[34:35], 0
	v_mov_b64 v[36:37], 0
	v_mov_b64 v[38:39], 0
	v_mov_b64 v[40:41], 0
	v_mov_b64 v[18:19], 0
	v_mov_b64 v[20:21], 0
	v_mov_b64 v[22:23], 0
	v_mov_b64 v[24:25], 0
	v_mov_b64 v[2:3], 0
	v_mov_b64 v[4:5], 0
	v_mov_b64 v[6:7], 0
	v_mov_b64 v[8:9], 0
	v_mov_b64 v[58:59], 0
	v_mov_b64 v[60:61], 0
	v_mov_b64 v[62:63], 0
	v_mov_b64 v[64:65], 0
	v_mov_b64 v[42:43], 0
	v_mov_b64 v[44:45], 0
	v_mov_b64 v[46:47], 0
	v_mov_b64 v[48:49], 0
	v_mov_b64 v[26:27], 0
	v_mov_b64 v[28:29], 0
	v_mov_b64 v[30:31], 0
	v_mov_b64 v[32:33], 0
	v_mov_b64 v[10:11], 0
	v_mov_b64 v[12:13], 0
	v_mov_b64 v[14:15], 0
	v_mov_b64 v[16:17], 0
	s_andn2_b64 vcc, exec, s[4:5]
	s_cbranch_vccnz .LBB0_392

.LBB0_460:
	v_add_u32_e32 v134, s95, v1
	ds_read_b128 v[130:133], v134
	ds_read_b128 v[136:139], v134 offset:1024
	ds_read_b128 v[140:143], v134 offset:2048
	ds_read_b128 v[144:147], v134 offset:3072
	v_add_u32_e32 v134, s93, v1
	ds_read_b128 v[170:173], v134
	ds_read_b128 v[200:203], v134 offset:1024
	ds_read_b128 v[204:207], v134 offset:2048
	ds_read_b128 v[208:211], v134 offset:3072
	s_add_u32 s8, s4, 0x10000
	s_addc_u32 s9, s5, 0
	s_cmp_eq_u32 s46, 12
	s_cselect_b32 s84, s41, s8
	s_cselect_b32 s85, s35, s9
	s_cselect_b32 s64, s43, s44
	s_cselect_b32 s65, s42, s45
	s_add_u32 s56, s84, 0x8000
	s_addc_u32 s57, s85, 0
	s_add_i32 m0, s69, 0xc000
	ds_read_b128 v[212:215], v194
	ds_read_b128 v[216:219], v194 offset:1024
	ds_read_b128 v[220:223], v194 offset:2048
	ds_read_b128 v[224:227], v194 offset:3072
	ds_read_b128 v[228:231], v194 offset:4096
	ds_read_b128 v[232:235], v194 offset:5120
	ds_read_b128 v[236:239], v194 offset:6144
	ds_read_b128 v[240:243], v194 offset:7168
	global_load_lds_dwordx4 v166, s[4:5] sc1
	s_add_i32 m0, s69, 0xe000
	s_nop 0
	global_load_lds_dwordx4 v168, s[4:5] sc1
	s_waitcnt vmcnt(8)
	s_waitcnt lgkmcnt(0)
	s_barrier
	s_setprio 1
	s_waitcnt lgkmcnt(0)
	v_mfma_f32_16x16x32_bf16 v[122:125], v[130:133], v[212:215], v[122:125]
	v_mfma_f32_16x16x32_bf16 v[126:129], v[140:143], v[212:215], v[126:129]
	v_mfma_f32_16x16x32_bf16 v[106:109], v[130:133], v[220:223], v[106:109]
	v_mfma_f32_16x16x32_bf16 v[110:113], v[140:143], v[220:223], v[110:113]
	v_mfma_f32_16x16x32_bf16 v[90:93], v[130:133], v[228:231], v[90:93]
	v_mfma_f32_16x16x32_bf16 v[94:97], v[140:143], v[228:231], v[94:97]
	v_mfma_f32_16x16x32_bf16 v[74:77], v[130:133], v[236:239], v[74:77]
	v_mfma_f32_16x16x32_bf16 v[78:81], v[140:143], v[236:239], v[78:81]
	v_mfma_f32_16x16x32_bf16 v[122:125], v[136:139], v[216:219], v[122:125]
	v_mfma_f32_16x16x32_bf16 v[126:129], v[144:147], v[216:219], v[126:129]
	v_mfma_f32_16x16x32_bf16 v[106:109], v[136:139], v[224:227], v[106:109]
	v_mfma_f32_16x16x32_bf16 v[110:113], v[144:147], v[224:227], v[110:113]
	v_mfma_f32_16x16x32_bf16 v[90:93], v[136:139], v[232:235], v[90:93]
	v_mfma_f32_16x16x32_bf16 v[94:97], v[144:147], v[232:235], v[94:97]
	v_mfma_f32_16x16x32_bf16 v[74:77], v[136:139], v[240:243], v[74:77]
	v_mfma_f32_16x16x32_bf16 v[78:81], v[144:147], v[240:243], v[78:81]
	s_setprio 0
	s_setprio 1
	v_mfma_f32_16x16x32_bf16 v[114:117], v[170:173], v[212:215], v[114:117]
	v_mfma_f32_16x16x32_bf16 v[118:121], v[204:207], v[212:215], v[118:121]
	v_mfma_f32_16x16x32_bf16 v[98:101], v[170:173], v[220:223], v[98:101]
	v_mfma_f32_16x16x32_bf16 v[102:105], v[204:207], v[220:223], v[102:105]
	v_mfma_f32_16x16x32_bf16 v[82:85], v[170:173], v[228:231], v[82:85]
	v_mfma_f32_16x16x32_bf16 v[86:89], v[204:207], v[228:231], v[86:89]
	v_mfma_f32_16x16x32_bf16 v[66:69], v[170:173], v[236:239], v[66:69]
	v_mfma_f32_16x16x32_bf16 v[70:73], v[204:207], v[236:239], v[70:73]
	v_mfma_f32_16x16x32_bf16 v[114:117], v[200:203], v[216:219], v[114:117]
	v_mfma_f32_16x16x32_bf16 v[118:121], v[208:211], v[216:219], v[118:121]
	v_mfma_f32_16x16x32_bf16 v[98:101], v[200:203], v[224:227], v[98:101]
	v_mfma_f32_16x16x32_bf16 v[102:105], v[208:211], v[224:227], v[102:105]
	v_mfma_f32_16x16x32_bf16 v[82:85], v[200:203], v[232:235], v[82:85]
	v_mfma_f32_16x16x32_bf16 v[86:89], v[208:211], v[232:235], v[86:89]
	v_mfma_f32_16x16x32_bf16 v[66:69], v[200:203], v[240:243], v[66:69]
	v_mfma_f32_16x16x32_bf16 v[70:73], v[208:211], v[240:243], v[70:73]
	s_setprio 0
	s_barrier
	s_add_i32 s4, s95, s61
	s_mov_b32 m0, s4
	ds_read_b128 v[212:215], v194 offset:16384
	ds_read_b128 v[216:219], v194 offset:17408
	ds_read_b128 v[220:223], v194 offset:18432
	ds_read_b128 v[224:227], v194 offset:19456
	ds_read_b128 v[228:231], v194 offset:20480
	ds_read_b128 v[232:235], v194 offset:21504
	ds_read_b128 v[236:239], v194 offset:22528
	ds_read_b128 v[240:243], v194 offset:23552
	global_load_lds_dwordx4 v152, s[64:65] sc1
	s_add_i32 m0, s4, 0x2000
	s_add_u32 s4, s64, 0x4000
	s_addc_u32 s5, s65, 0
	s_add_i32 s47, s93, s61
	global_load_lds_dwordx4 v154, s[64:65] sc1
	s_mov_b32 m0, s47
	s_nop 0
	global_load_lds_dwordx4 v152, s[4:5] sc1
	s_add_i32 m0, s47, 0x2000
	s_nop 0
	global_load_lds_dwordx4 v154, s[4:5] sc1
	s_mov_b32 m0, s69
	s_nop 0
	global_load_lds_dwordx4 v150, s[84:85] sc1
	s_mov_b32 m0, s77
	s_nop 0
	global_load_lds_dwordx4 v148, s[84:85] sc1
	s_waitcnt vmcnt(8)
	s_waitcnt lgkmcnt(0)
	s_barrier
	s_setprio 1
	s_waitcnt lgkmcnt(0)
	v_mfma_f32_16x16x32_bf16 v[58:61], v[130:133], v[212:215], v[58:61]
	v_mfma_f32_16x16x32_bf16 v[62:65], v[140:143], v[212:215], v[62:65]
	v_mfma_f32_16x16x32_bf16 v[42:45], v[130:133], v[220:223], v[42:45]
	v_mfma_f32_16x16x32_bf16 v[46:49], v[140:143], v[220:223], v[46:49]
	v_mfma_f32_16x16x32_bf16 v[26:29], v[130:133], v[228:231], v[26:29]
	v_mfma_f32_16x16x32_bf16 v[30:33], v[140:143], v[228:231], v[30:33]
	v_mfma_f32_16x16x32_bf16 v[10:13], v[130:133], v[236:239], v[10:13]
	v_mfma_f32_16x16x32_bf16 v[14:17], v[140:143], v[236:239], v[14:17]
	v_mfma_f32_16x16x32_bf16 v[58:61], v[136:139], v[216:219], v[58:61]
	v_mfma_f32_16x16x32_bf16 v[62:65], v[144:147], v[216:219], v[62:65]
	v_mfma_f32_16x16x32_bf16 v[42:45], v[136:139], v[224:227], v[42:45]
	v_mfma_f32_16x16x32_bf16 v[46:49], v[144:147], v[224:227], v[46:49]
	v_mfma_f32_16x16x32_bf16 v[26:29], v[136:139], v[232:235], v[26:29]
	v_mfma_f32_16x16x32_bf16 v[30:33], v[144:147], v[232:235], v[30:33]
	v_mfma_f32_16x16x32_bf16 v[10:13], v[136:139], v[240:243], v[10:13]
	v_mfma_f32_16x16x32_bf16 v[14:17], v[144:147], v[240:243], v[14:17]
	s_setprio 0
	s_setprio 1
	v_mfma_f32_16x16x32_bf16 v[50:53], v[170:173], v[212:215], v[50:53]
	v_mfma_f32_16x16x32_bf16 v[54:57], v[204:207], v[212:215], v[54:57]
	v_mfma_f32_16x16x32_bf16 v[34:37], v[170:173], v[220:223], v[34:37]
	v_mfma_f32_16x16x32_bf16 v[38:41], v[204:207], v[220:223], v[38:41]
	v_mfma_f32_16x16x32_bf16 v[18:21], v[170:173], v[228:231], v[18:21]
	v_mfma_f32_16x16x32_bf16 v[22:25], v[204:207], v[228:231], v[22:25]
	v_mfma_f32_16x16x32_bf16 v[2:5], v[170:173], v[236:239], v[2:5]
	v_mfma_f32_16x16x32_bf16 v[6:9], v[204:207], v[236:239], v[6:9]
	v_mfma_f32_16x16x32_bf16 v[50:53], v[200:203], v[216:219], v[50:53]
	v_mfma_f32_16x16x32_bf16 v[54:57], v[208:211], v[216:219], v[54:57]
	v_mfma_f32_16x16x32_bf16 v[34:37], v[200:203], v[224:227], v[34:37]
	v_mfma_f32_16x16x32_bf16 v[38:41], v[208:211], v[224:227], v[38:41]
	v_mfma_f32_16x16x32_bf16 v[18:21], v[200:203], v[232:235], v[18:21]
	v_mfma_f32_16x16x32_bf16 v[22:25], v[208:211], v[232:235], v[22:25]
	v_mfma_f32_16x16x32_bf16 v[2:5], v[200:203], v[240:243], v[2:5]
	v_mfma_f32_16x16x32_bf16 v[6:9], v[208:211], v[240:243], v[6:9]
	s_setprio 0
	s_barrier
	v_add_u32_e32 v134, s36, v1
	ds_read_b128 v[130:133], v134
	ds_read_b128 v[136:139], v134 offset:1024
	ds_read_b128 v[140:143], v134 offset:2048
	ds_read_b128 v[144:147], v134 offset:3072
	v_add_u32_e32 v134, s37, v1
	ds_read_b128 v[170:173], v134
	ds_read_b128 v[200:203], v134 offset:1024
	ds_read_b128 v[204:207], v134 offset:2048
	ds_read_b128 v[208:211], v134 offset:3072
	s_add_u32 s4, s84, 0x4000
	s_addc_u32 s5, s85, 0
	s_mov_b32 m0, s86
	ds_read_b128 v[212:215], v194 offset:32768
	ds_read_b128 v[216:219], v194 offset:33792
	ds_read_b128 v[220:223], v194 offset:34816
	ds_read_b128 v[224:227], v194 offset:35840
	ds_read_b128 v[228:231], v194 offset:36864
	ds_read_b128 v[232:235], v194 offset:37888
	ds_read_b128 v[236:239], v194 offset:38912
	ds_read_b128 v[240:243], v194 offset:39936
	global_load_lds_dwordx4 v150, s[4:5] sc1
	s_mov_b32 m0, s87
	s_nop 0
	global_load_lds_dwordx4 v148, s[4:5] sc1
	s_waitcnt vmcnt(8)
	s_waitcnt lgkmcnt(0)
	s_barrier
	s_setprio 1
	s_waitcnt lgkmcnt(0)
	v_mfma_f32_16x16x32_bf16 v[122:125], v[130:133], v[212:215], v[122:125]
	v_mfma_f32_16x16x32_bf16 v[126:129], v[140:143], v[212:215], v[126:129]
	v_mfma_f32_16x16x32_bf16 v[106:109], v[130:133], v[220:223], v[106:109]
	v_mfma_f32_16x16x32_bf16 v[110:113], v[140:143], v[220:223], v[110:113]
	v_mfma_f32_16x16x32_bf16 v[90:93], v[130:133], v[228:231], v[90:93]
	v_mfma_f32_16x16x32_bf16 v[94:97], v[140:143], v[228:231], v[94:97]
	v_mfma_f32_16x16x32_bf16 v[74:77], v[130:133], v[236:239], v[74:77]
	v_mfma_f32_16x16x32_bf16 v[78:81], v[140:143], v[236:239], v[78:81]
	v_mfma_f32_16x16x32_bf16 v[122:125], v[136:139], v[216:219], v[122:125]
	v_mfma_f32_16x16x32_bf16 v[126:129], v[144:147], v[216:219], v[126:129]
	v_mfma_f32_16x16x32_bf16 v[106:109], v[136:139], v[224:227], v[106:109]
	v_mfma_f32_16x16x32_bf16 v[110:113], v[144:147], v[224:227], v[110:113]
	v_mfma_f32_16x16x32_bf16 v[90:93], v[136:139], v[232:235], v[90:93]
	v_mfma_f32_16x16x32_bf16 v[94:97], v[144:147], v[232:235], v[94:97]
	v_mfma_f32_16x16x32_bf16 v[74:77], v[136:139], v[240:243], v[74:77]
	v_mfma_f32_16x16x32_bf16 v[78:81], v[144:147], v[240:243], v[78:81]
	s_setprio 0
	s_setprio 1
	v_mfma_f32_16x16x32_bf16 v[114:117], v[170:173], v[212:215], v[114:117]
	v_mfma_f32_16x16x32_bf16 v[118:121], v[204:207], v[212:215], v[118:121]
	v_mfma_f32_16x16x32_bf16 v[98:101], v[170:173], v[220:223], v[98:101]
	v_mfma_f32_16x16x32_bf16 v[102:105], v[204:207], v[220:223], v[102:105]
	v_mfma_f32_16x16x32_bf16 v[82:85], v[170:173], v[228:231], v[82:85]
	v_mfma_f32_16x16x32_bf16 v[86:89], v[204:207], v[228:231], v[86:89]
	v_mfma_f32_16x16x32_bf16 v[66:69], v[170:173], v[236:239], v[66:69]
	v_mfma_f32_16x16x32_bf16 v[70:73], v[204:207], v[236:239], v[70:73]
	v_mfma_f32_16x16x32_bf16 v[114:117], v[200:203], v[216:219], v[114:117]
	v_mfma_f32_16x16x32_bf16 v[118:121], v[208:211], v[216:219], v[118:121]
	v_mfma_f32_16x16x32_bf16 v[98:101], v[200:203], v[224:227], v[98:101]
	v_mfma_f32_16x16x32_bf16 v[102:105], v[208:211], v[224:227], v[102:105]
	v_mfma_f32_16x16x32_bf16 v[82:85], v[200:203], v[232:235], v[82:85]
	v_mfma_f32_16x16x32_bf16 v[86:89], v[208:211], v[232:235], v[86:89]
	v_mfma_f32_16x16x32_bf16 v[66:69], v[200:203], v[240:243], v[66:69]
	v_mfma_f32_16x16x32_bf16 v[70:73], v[208:211], v[240:243], v[70:73]
	s_setprio 0
	s_barrier
	s_add_u32 s4, s64, 0x8000
	s_addc_u32 s5, s65, 0
	s_add_i32 s47, s36, s61
	s_mov_b32 m0, s47
	ds_read_b128 v[212:215], v194 offset:49152
	ds_read_b128 v[216:219], v194 offset:50176
	ds_read_b128 v[220:223], v194 offset:51200
	ds_read_b128 v[224:227], v194 offset:52224
	ds_read_b128 v[228:231], v194 offset:53248
	ds_read_b128 v[232:235], v194 offset:54272
	ds_read_b128 v[236:239], v194 offset:55296
	ds_read_b128 v[240:243], v194 offset:56320
	global_load_lds_dwordx4 v152, s[4:5] sc1
	s_add_i32 m0, s47, 0x2000
	s_nop 0
	global_load_lds_dwordx4 v154, s[4:5] sc1
	s_add_u32 s4, s64, 0xc000
	s_addc_u32 s5, s65, 0
	s_add_i32 s47, s37, s61
	s_mov_b32 m0, s47
	s_nop 0
	global_load_lds_dwordx4 v152, s[4:5] sc1
	s_add_i32 m0, s47, 0x2000
	s_nop 0
	global_load_lds_dwordx4 v154, s[4:5] sc1
	s_mov_b32 m0, s91
	s_nop 0
	global_load_lds_dwordx4 v150, s[56:57] sc1
	s_mov_b32 m0, s92
	s_nop 0
	global_load_lds_dwordx4 v148, s[56:57] sc1
	s_waitcnt vmcnt(8)
	s_waitcnt lgkmcnt(0)
	s_barrier
	s_setprio 1
	s_waitcnt lgkmcnt(0)
	v_mfma_f32_16x16x32_bf16 v[58:61], v[130:133], v[212:215], v[58:61]
	v_mfma_f32_16x16x32_bf16 v[62:65], v[140:143], v[212:215], v[62:65]
	v_mfma_f32_16x16x32_bf16 v[42:45], v[130:133], v[220:223], v[42:45]
	v_mfma_f32_16x16x32_bf16 v[46:49], v[140:143], v[220:223], v[46:49]
	v_mfma_f32_16x16x32_bf16 v[26:29], v[130:133], v[228:231], v[26:29]
	v_mfma_f32_16x16x32_bf16 v[30:33], v[140:143], v[228:231], v[30:33]
	v_mfma_f32_16x16x32_bf16 v[10:13], v[130:133], v[236:239], v[10:13]
	v_mfma_f32_16x16x32_bf16 v[14:17], v[140:143], v[236:239], v[14:17]
	v_mfma_f32_16x16x32_bf16 v[58:61], v[136:139], v[216:219], v[58:61]
	v_mfma_f32_16x16x32_bf16 v[62:65], v[144:147], v[216:219], v[62:65]
	v_mfma_f32_16x16x32_bf16 v[42:45], v[136:139], v[224:227], v[42:45]
	v_mfma_f32_16x16x32_bf16 v[46:49], v[144:147], v[224:227], v[46:49]
	v_mfma_f32_16x16x32_bf16 v[26:29], v[136:139], v[232:235], v[26:29]
	v_mfma_f32_16x16x32_bf16 v[30:33], v[144:147], v[232:235], v[30:33]
	v_mfma_f32_16x16x32_bf16 v[10:13], v[136:139], v[240:243], v[10:13]
	v_mfma_f32_16x16x32_bf16 v[14:17], v[144:147], v[240:243], v[14:17]
	s_setprio 0
	s_setprio 1
	v_mfma_f32_16x16x32_bf16 v[50:53], v[170:173], v[212:215], v[50:53]
	v_mfma_f32_16x16x32_bf16 v[54:57], v[204:207], v[212:215], v[54:57]
	v_mfma_f32_16x16x32_bf16 v[34:37], v[170:173], v[220:223], v[34:37]
	v_mfma_f32_16x16x32_bf16 v[38:41], v[204:207], v[220:223], v[38:41]
	v_mfma_f32_16x16x32_bf16 v[18:21], v[170:173], v[228:231], v[18:21]
	v_mfma_f32_16x16x32_bf16 v[22:25], v[204:207], v[228:231], v[22:25]
	v_mfma_f32_16x16x32_bf16 v[2:5], v[170:173], v[236:239], v[2:5]
	v_mfma_f32_16x16x32_bf16 v[6:9], v[204:207], v[236:239], v[6:9]
	v_mfma_f32_16x16x32_bf16 v[50:53], v[200:203], v[216:219], v[50:53]
	v_mfma_f32_16x16x32_bf16 v[54:57], v[208:211], v[216:219], v[54:57]
	v_mfma_f32_16x16x32_bf16 v[34:37], v[200:203], v[224:227], v[34:37]
	v_mfma_f32_16x16x32_bf16 v[38:41], v[208:211], v[224:227], v[38:41]
	v_mfma_f32_16x16x32_bf16 v[18:21], v[200:203], v[232:235], v[18:21]
	v_mfma_f32_16x16x32_bf16 v[22:25], v[208:211], v[232:235], v[22:25]
	v_mfma_f32_16x16x32_bf16 v[2:5], v[200:203], v[240:243], v[2:5]
	v_mfma_f32_16x16x32_bf16 v[6:9], v[208:211], v[240:243], v[6:9]
	s_setprio 0
	s_barrier
	s_add_i32 s46, s46, 2
	s_add_u32 s44, s44, 0x10000
	s_addc_u32 s45, s45, 0
	s_cmp_gt_u32 s46, 13
	s_mov_b64 s[4:5], s[8:9]
	s_cbranch_scc0 .LBB0_460
	s_and_b64 vcc, exec, s[70:71]
	s_cbranch_vccz .LBB0_463
	s_barrier

.LBB0_623:
	v_add_u32_e32 v160, s47, v142
	ds_read_b128 v[152:155], v160
	ds_read_b128 v[156:159], v160 offset:1024
	ds_read_b128 v[162:165], v160 offset:2048
	ds_read_b128 v[166:169], v160 offset:3072
	v_add_u32_e32 v160, s48, v142
	ds_read_b128 v[170:173], v160
	ds_read_b128 v[174:177], v160 offset:1024
	ds_read_b128 v[178:181], v160 offset:2048
	ds_read_b128 v[182:185], v160 offset:3072
	s_add_u32 s78, s70, 0x10000
	s_addc_u32 s79, s71, 0
	s_cmp_eq_u32 s94, 12
	s_cselect_b32 s92, s57, s78
	s_cselect_b32 s93, s55, s79
	s_cselect_b32 s90, s61, s69
	s_cselect_b32 s91, s11, s77
	s_add_u32 s82, s92, 0x8000
	s_addc_u32 s83, s93, 0
	s_add_i32 m0, s39, 0xc000
	ds_read_b128 v[192:195], v150
	ds_read_b128 v[200:203], v150 offset:1024
	ds_read_b128 v[204:207], v150 offset:2048
	ds_read_b128 v[208:211], v150 offset:3072
	ds_read_b128 v[212:215], v150 offset:4096
	ds_read_b128 v[216:219], v150 offset:5120
	ds_read_b128 v[220:223], v150 offset:6144
	ds_read_b128 v[224:227], v150 offset:7168
	global_load_lds_dwordx4 v138, s[70:71] sc1
	s_add_i32 m0, s39, 0xe000
	s_nop 0
	global_load_lds_dwordx4 v140, s[70:71] sc1
	s_waitcnt vmcnt(8)
	s_waitcnt lgkmcnt(0)
	s_barrier
	s_setprio 1
	s_waitcnt lgkmcnt(0)
	v_mfma_f32_16x16x32_bf16 v[98:101], v[152:155], v[192:195], v[98:101]
	v_mfma_f32_16x16x32_bf16 v[102:105], v[162:165], v[192:195], v[102:105]
	v_mfma_f32_16x16x32_bf16 v[62:65], v[152:155], v[204:207], v[62:65]
	v_mfma_f32_16x16x32_bf16 v[78:81], v[162:165], v[204:207], v[78:81]
	v_mfma_f32_16x16x32_bf16 v[34:37], v[152:155], v[212:215], v[34:37]
	v_mfma_f32_16x16x32_bf16 v[46:49], v[162:165], v[212:215], v[46:49]
	v_mfma_f32_16x16x32_bf16 v[14:17], v[152:155], v[220:223], v[14:17]
	v_mfma_f32_16x16x32_bf16 v[22:25], v[162:165], v[220:223], v[22:25]
	v_mfma_f32_16x16x32_bf16 v[98:101], v[156:159], v[200:203], v[98:101]
	v_mfma_f32_16x16x32_bf16 v[102:105], v[166:169], v[200:203], v[102:105]
	v_mfma_f32_16x16x32_bf16 v[62:65], v[156:159], v[208:211], v[62:65]
	v_mfma_f32_16x16x32_bf16 v[78:81], v[166:169], v[208:211], v[78:81]
	v_mfma_f32_16x16x32_bf16 v[34:37], v[156:159], v[216:219], v[34:37]
	v_mfma_f32_16x16x32_bf16 v[46:49], v[166:169], v[216:219], v[46:49]
	v_mfma_f32_16x16x32_bf16 v[14:17], v[156:159], v[224:227], v[14:17]
	v_mfma_f32_16x16x32_bf16 v[22:25], v[166:169], v[224:227], v[22:25]
	s_setprio 0
	s_setprio 1
	v_mfma_f32_16x16x32_bf16 v[122:125], v[170:173], v[192:195], v[122:125]
	v_mfma_f32_16x16x32_bf16 v[126:129], v[178:181], v[192:195], v[126:129]
	v_mfma_f32_16x16x32_bf16 v[110:113], v[170:173], v[204:207], v[110:113]
	v_mfma_f32_16x16x32_bf16 v[118:121], v[178:181], v[204:207], v[118:121]
	v_mfma_f32_16x16x32_bf16 v[86:89], v[170:173], v[212:215], v[86:89]
	v_mfma_f32_16x16x32_bf16 v[94:97], v[178:181], v[212:215], v[94:97]
	v_mfma_f32_16x16x32_bf16 v[54:57], v[170:173], v[220:223], v[54:57]
	v_mfma_f32_16x16x32_bf16 v[70:73], v[178:181], v[220:223], v[70:73]
	v_mfma_f32_16x16x32_bf16 v[122:125], v[174:177], v[200:203], v[122:125]
	v_mfma_f32_16x16x32_bf16 v[126:129], v[182:185], v[200:203], v[126:129]
	v_mfma_f32_16x16x32_bf16 v[110:113], v[174:177], v[208:211], v[110:113]
	v_mfma_f32_16x16x32_bf16 v[118:121], v[182:185], v[208:211], v[118:121]
	v_mfma_f32_16x16x32_bf16 v[86:89], v[174:177], v[216:219], v[86:89]
	v_mfma_f32_16x16x32_bf16 v[94:97], v[182:185], v[216:219], v[94:97]
	v_mfma_f32_16x16x32_bf16 v[54:57], v[174:177], v[224:227], v[54:57]
	v_mfma_f32_16x16x32_bf16 v[70:73], v[182:185], v[224:227], v[70:73]
	s_setprio 0
	s_barrier
	s_add_i32 s70, s47, s35
	s_mov_b32 m0, s70
	ds_read_b128 v[192:195], v150 offset:16384
	ds_read_b128 v[200:203], v150 offset:17408
	ds_read_b128 v[204:207], v150 offset:18432
	ds_read_b128 v[208:211], v150 offset:19456
	ds_read_b128 v[212:215], v150 offset:20480
	ds_read_b128 v[216:219], v150 offset:21504
	ds_read_b128 v[220:223], v150 offset:22528
	ds_read_b128 v[224:227], v150 offset:23552
	global_load_lds_dwordx4 v132, s[90:91] sc1
	s_add_i32 m0, s70, 0x2000
	s_add_u32 s70, s90, 0x4000
	s_addc_u32 s71, s91, 0
	s_add_i32 s95, s48, s35
	global_load_lds_dwordx4 v136, s[90:91] sc1
	s_mov_b32 m0, s95
	s_nop 0
	global_load_lds_dwordx4 v132, s[70:71] sc1
	s_add_i32 m0, s95, 0x2000
	s_nop 0
	global_load_lds_dwordx4 v136, s[70:71] sc1
	s_mov_b32 m0, s39
	s_nop 0
	global_load_lds_dwordx4 v130, s[92:93] sc1
	s_mov_b32 m0, s40
	s_nop 0
	global_load_lds_dwordx4 v134, s[92:93] sc1
	s_waitcnt vmcnt(8)
	s_waitcnt lgkmcnt(0)
	s_barrier
	s_setprio 1
	s_waitcnt lgkmcnt(0)
	v_mfma_f32_16x16x32_bf16 v[58:61], v[152:155], v[192:195], v[58:61]
	v_mfma_f32_16x16x32_bf16 v[74:77], v[162:165], v[192:195], v[74:77]
	v_mfma_f32_16x16x32_bf16 v[30:33], v[152:155], v[204:207], v[30:33]
	v_mfma_f32_16x16x32_bf16 v[42:45], v[162:165], v[204:207], v[42:45]
	v_mfma_f32_16x16x32_bf16 v[10:13], v[152:155], v[212:215], v[10:13]
	v_mfma_f32_16x16x32_bf16 v[18:21], v[162:165], v[212:215], v[18:21]
	v_mfma_f32_16x16x32_bf16 v[2:5], v[152:155], v[220:223], v[2:5]
	v_mfma_f32_16x16x32_bf16 v[6:9], v[162:165], v[220:223], v[6:9]
	v_mfma_f32_16x16x32_bf16 v[58:61], v[156:159], v[200:203], v[58:61]
	v_mfma_f32_16x16x32_bf16 v[74:77], v[166:169], v[200:203], v[74:77]
	v_mfma_f32_16x16x32_bf16 v[30:33], v[156:159], v[208:211], v[30:33]
	v_mfma_f32_16x16x32_bf16 v[42:45], v[166:169], v[208:211], v[42:45]
	v_mfma_f32_16x16x32_bf16 v[10:13], v[156:159], v[216:219], v[10:13]
	v_mfma_f32_16x16x32_bf16 v[18:21], v[166:169], v[216:219], v[18:21]
	v_mfma_f32_16x16x32_bf16 v[2:5], v[156:159], v[224:227], v[2:5]
	v_mfma_f32_16x16x32_bf16 v[6:9], v[166:169], v[224:227], v[6:9]
	s_setprio 0
	s_setprio 1
	v_mfma_f32_16x16x32_bf16 v[106:109], v[170:173], v[192:195], v[106:109]
	v_mfma_f32_16x16x32_bf16 v[114:117], v[178:181], v[192:195], v[114:117]
	v_mfma_f32_16x16x32_bf16 v[82:85], v[170:173], v[204:207], v[82:85]
	v_mfma_f32_16x16x32_bf16 v[90:93], v[178:181], v[204:207], v[90:93]
	v_mfma_f32_16x16x32_bf16 v[50:53], v[170:173], v[212:215], v[50:53]
	v_mfma_f32_16x16x32_bf16 v[66:69], v[178:181], v[212:215], v[66:69]
	v_mfma_f32_16x16x32_bf16 v[26:29], v[170:173], v[220:223], v[26:29]
	v_mfma_f32_16x16x32_bf16 v[38:41], v[178:181], v[220:223], v[38:41]
	v_mfma_f32_16x16x32_bf16 v[106:109], v[174:177], v[200:203], v[106:109]
	v_mfma_f32_16x16x32_bf16 v[114:117], v[182:185], v[200:203], v[114:117]
	v_mfma_f32_16x16x32_bf16 v[82:85], v[174:177], v[208:211], v[82:85]
	v_mfma_f32_16x16x32_bf16 v[90:93], v[182:185], v[208:211], v[90:93]
	v_mfma_f32_16x16x32_bf16 v[50:53], v[174:177], v[216:219], v[50:53]
	v_mfma_f32_16x16x32_bf16 v[66:69], v[182:185], v[216:219], v[66:69]
	v_mfma_f32_16x16x32_bf16 v[26:29], v[174:177], v[224:227], v[26:29]
	v_mfma_f32_16x16x32_bf16 v[38:41], v[182:185], v[224:227], v[38:41]
	s_setprio 0
	s_barrier
	v_add_u32_e32 v160, s49, v142
	ds_read_b128 v[152:155], v160
	ds_read_b128 v[156:159], v160 offset:1024
	ds_read_b128 v[162:165], v160 offset:2048
	ds_read_b128 v[166:169], v160 offset:3072
	v_add_u32_e32 v160, s50, v142
	ds_read_b128 v[170:173], v160
	ds_read_b128 v[174:177], v160 offset:1024
	ds_read_b128 v[178:181], v160 offset:2048
	ds_read_b128 v[182:185], v160 offset:3072
	s_add_u32 s70, s92, 0x4000
	s_addc_u32 s71, s93, 0
	s_mov_b32 m0, s41
	ds_read_b128 v[192:195], v150 offset:32768
	ds_read_b128 v[200:203], v150 offset:33792
	ds_read_b128 v[204:207], v150 offset:34816
	ds_read_b128 v[208:211], v150 offset:35840
	ds_read_b128 v[212:215], v150 offset:36864
	ds_read_b128 v[216:219], v150 offset:37888
	ds_read_b128 v[220:223], v150 offset:38912
	ds_read_b128 v[224:227], v150 offset:39936
	global_load_lds_dwordx4 v130, s[70:71] sc1
	s_mov_b32 m0, s42
	s_nop 0
	global_load_lds_dwordx4 v134, s[70:71] sc1
	s_waitcnt vmcnt(8)
	s_waitcnt lgkmcnt(0)
	s_barrier
	s_setprio 1
	s_waitcnt lgkmcnt(0)
	v_mfma_f32_16x16x32_bf16 v[98:101], v[152:155], v[192:195], v[98:101]
	v_mfma_f32_16x16x32_bf16 v[102:105], v[162:165], v[192:195], v[102:105]
	v_mfma_f32_16x16x32_bf16 v[62:65], v[152:155], v[204:207], v[62:65]
	v_mfma_f32_16x16x32_bf16 v[78:81], v[162:165], v[204:207], v[78:81]
	v_mfma_f32_16x16x32_bf16 v[34:37], v[152:155], v[212:215], v[34:37]
	v_mfma_f32_16x16x32_bf16 v[46:49], v[162:165], v[212:215], v[46:49]
	v_mfma_f32_16x16x32_bf16 v[14:17], v[152:155], v[220:223], v[14:17]
	v_mfma_f32_16x16x32_bf16 v[22:25], v[162:165], v[220:223], v[22:25]
	v_mfma_f32_16x16x32_bf16 v[98:101], v[156:159], v[200:203], v[98:101]
	v_mfma_f32_16x16x32_bf16 v[102:105], v[166:169], v[200:203], v[102:105]
	v_mfma_f32_16x16x32_bf16 v[62:65], v[156:159], v[208:211], v[62:65]
	v_mfma_f32_16x16x32_bf16 v[78:81], v[166:169], v[208:211], v[78:81]
	v_mfma_f32_16x16x32_bf16 v[34:37], v[156:159], v[216:219], v[34:37]
	v_mfma_f32_16x16x32_bf16 v[46:49], v[166:169], v[216:219], v[46:49]
	v_mfma_f32_16x16x32_bf16 v[14:17], v[156:159], v[224:227], v[14:17]
	v_mfma_f32_16x16x32_bf16 v[22:25], v[166:169], v[224:227], v[22:25]
	s_setprio 0
	s_setprio 1
	v_mfma_f32_16x16x32_bf16 v[122:125], v[170:173], v[192:195], v[122:125]
	v_mfma_f32_16x16x32_bf16 v[126:129], v[178:181], v[192:195], v[126:129]
	v_mfma_f32_16x16x32_bf16 v[110:113], v[170:173], v[204:207], v[110:113]
	v_mfma_f32_16x16x32_bf16 v[118:121], v[178:181], v[204:207], v[118:121]
	v_mfma_f32_16x16x32_bf16 v[86:89], v[170:173], v[212:215], v[86:89]
	v_mfma_f32_16x16x32_bf16 v[94:97], v[178:181], v[212:215], v[94:97]
	v_mfma_f32_16x16x32_bf16 v[54:57], v[170:173], v[220:223], v[54:57]
	v_mfma_f32_16x16x32_bf16 v[70:73], v[178:181], v[220:223], v[70:73]
	v_mfma_f32_16x16x32_bf16 v[122:125], v[174:177], v[200:203], v[122:125]
	v_mfma_f32_16x16x32_bf16 v[126:129], v[182:185], v[200:203], v[126:129]
	v_mfma_f32_16x16x32_bf16 v[110:113], v[174:177], v[208:211], v[110:113]
	v_mfma_f32_16x16x32_bf16 v[118:121], v[182:185], v[208:211], v[118:121]
	v_mfma_f32_16x16x32_bf16 v[86:89], v[174:177], v[216:219], v[86:89]
	v_mfma_f32_16x16x32_bf16 v[94:97], v[182:185], v[216:219], v[94:97]
	v_mfma_f32_16x16x32_bf16 v[54:57], v[174:177], v[224:227], v[54:57]
	v_mfma_f32_16x16x32_bf16 v[70:73], v[182:185], v[224:227], v[70:73]
	s_setprio 0
	s_barrier
	s_add_u32 s70, s90, 0x8000
	s_addc_u32 s71, s91, 0
	s_add_i32 s92, s49, s35
	s_mov_b32 m0, s92
	ds_read_b128 v[192:195], v150 offset:49152
	ds_read_b128 v[200:203], v150 offset:50176
	ds_read_b128 v[204:207], v150 offset:51200
	ds_read_b128 v[208:211], v150 offset:52224
	ds_read_b128 v[212:215], v150 offset:53248
	ds_read_b128 v[216:219], v150 offset:54272
	ds_read_b128 v[220:223], v150 offset:55296
	ds_read_b128 v[224:227], v150 offset:56320
	global_load_lds_dwordx4 v132, s[70:71] sc1
	s_add_i32 m0, s92, 0x2000
	s_nop 0
	global_load_lds_dwordx4 v136, s[70:71] sc1
	s_add_u32 s70, s90, 0xc000
	s_addc_u32 s71, s91, 0
	s_add_i32 s90, s50, s35
	s_mov_b32 m0, s90
	s_nop 0
	global_load_lds_dwordx4 v132, s[70:71] sc1
	s_add_i32 m0, s90, 0x2000
	s_nop 0
	global_load_lds_dwordx4 v136, s[70:71] sc1
	s_mov_b32 m0, s44
	s_nop 0
	global_load_lds_dwordx4 v130, s[82:83] sc1
	s_mov_b32 m0, s45
	s_nop 0
	global_load_lds_dwordx4 v134, s[82:83] sc1
	s_waitcnt vmcnt(8)
	s_waitcnt lgkmcnt(0)
	s_barrier
	s_setprio 1
	s_waitcnt lgkmcnt(0)
	v_mfma_f32_16x16x32_bf16 v[58:61], v[152:155], v[192:195], v[58:61]
	v_mfma_f32_16x16x32_bf16 v[74:77], v[162:165], v[192:195], v[74:77]
	v_mfma_f32_16x16x32_bf16 v[30:33], v[152:155], v[204:207], v[30:33]
	v_mfma_f32_16x16x32_bf16 v[42:45], v[162:165], v[204:207], v[42:45]
	v_mfma_f32_16x16x32_bf16 v[10:13], v[152:155], v[212:215], v[10:13]
	v_mfma_f32_16x16x32_bf16 v[18:21], v[162:165], v[212:215], v[18:21]
	v_mfma_f32_16x16x32_bf16 v[2:5], v[152:155], v[220:223], v[2:5]
	v_mfma_f32_16x16x32_bf16 v[6:9], v[162:165], v[220:223], v[6:9]
	v_mfma_f32_16x16x32_bf16 v[58:61], v[156:159], v[200:203], v[58:61]
	v_mfma_f32_16x16x32_bf16 v[74:77], v[166:169], v[200:203], v[74:77]
	v_mfma_f32_16x16x32_bf16 v[30:33], v[156:159], v[208:211], v[30:33]
	v_mfma_f32_16x16x32_bf16 v[42:45], v[166:169], v[208:211], v[42:45]
	v_mfma_f32_16x16x32_bf16 v[10:13], v[156:159], v[216:219], v[10:13]
	v_mfma_f32_16x16x32_bf16 v[18:21], v[166:169], v[216:219], v[18:21]
	v_mfma_f32_16x16x32_bf16 v[2:5], v[156:159], v[224:227], v[2:5]
	v_mfma_f32_16x16x32_bf16 v[6:9], v[166:169], v[224:227], v[6:9]
	s_setprio 0
	s_setprio 1
	v_mfma_f32_16x16x32_bf16 v[106:109], v[170:173], v[192:195], v[106:109]
	v_mfma_f32_16x16x32_bf16 v[114:117], v[178:181], v[192:195], v[114:117]
	v_mfma_f32_16x16x32_bf16 v[82:85], v[170:173], v[204:207], v[82:85]
	v_mfma_f32_16x16x32_bf16 v[90:93], v[178:181], v[204:207], v[90:93]
	v_mfma_f32_16x16x32_bf16 v[50:53], v[170:173], v[212:215], v[50:53]
	v_mfma_f32_16x16x32_bf16 v[66:69], v[178:181], v[212:215], v[66:69]
	v_mfma_f32_16x16x32_bf16 v[26:29], v[170:173], v[220:223], v[26:29]
	v_mfma_f32_16x16x32_bf16 v[38:41], v[178:181], v[220:223], v[38:41]
	v_mfma_f32_16x16x32_bf16 v[106:109], v[174:177], v[200:203], v[106:109]
	v_mfma_f32_16x16x32_bf16 v[114:117], v[182:185], v[200:203], v[114:117]
	v_mfma_f32_16x16x32_bf16 v[82:85], v[174:177], v[208:211], v[82:85]
	v_mfma_f32_16x16x32_bf16 v[90:93], v[182:185], v[208:211], v[90:93]
	v_mfma_f32_16x16x32_bf16 v[50:53], v[174:177], v[216:219], v[50:53]
	v_mfma_f32_16x16x32_bf16 v[66:69], v[182:185], v[216:219], v[66:69]
	v_mfma_f32_16x16x32_bf16 v[26:29], v[174:177], v[224:227], v[26:29]
	v_mfma_f32_16x16x32_bf16 v[38:41], v[182:185], v[224:227], v[38:41]
	s_setprio 0
	s_barrier
	s_add_i32 s94, s94, 2
	s_add_u32 s69, s69, 0x10000
	s_addc_u32 s77, s77, 0
	s_cmp_gt_u32 s94, 13
	s_mov_b64 s[70:71], s[78:79]
	s_cbranch_scc0 .LBB0_623
	s_and_b64 vcc, exec, s[8:9]
	s_cbranch_vccz .LBB0_626
	s_barrier

.LBB0_884:
	s_add_u32 s19, s38, s64
	s_addc_u32 s41, s39, s65
	v_add_u32_e32 v168, s49, v151
	v_add_u32_e32 v184, s51, v151
	s_add_u32 s19, s19, 0x10000
	ds_read_b128 v[156:159], v168
	ds_read_b128 v[160:163], v168 offset:1024
	ds_read_b128 v[164:167], v168 offset:2048
	ds_read_b128 v[168:171], v168 offset:3072
	ds_read_b128 v[172:175], v184
	ds_read_b128 v[176:179], v184 offset:1024
	ds_read_b128 v[180:183], v184 offset:2048
	ds_read_b128 v[184:187], v184 offset:3072
	s_addc_u32 s41, s41, 0
	s_add_u32 s66, s69, s64
	s_addc_u32 s67, s80, s65
	s_cmp_eq_u32 s64, 0x70000
	s_cselect_b32 s78, s81, s19
	s_cselect_b32 s79, s57, s41
	s_cselect_b32 s70, s86, s66
	s_cselect_b32 s71, s85, s67
	s_add_u32 s66, s78, 0x8000
	s_addc_u32 s67, s79, 0
	s_add_i32 s19, s37, 0xc000
	v_lshl_add_u64 v[196:197], v[144:145], 0, s[64:65]
	s_mov_b32 m0, s19
	s_add_i32 s41, s37, 0xe000
	ds_read_b128 v[192:195], v154
	ds_read_b128 v[200:203], v154 offset:1024
	ds_read_b128 v[204:207], v154 offset:2048
	ds_read_b128 v[208:211], v154 offset:3072
	ds_read_b128 v[212:215], v154 offset:4096
	ds_read_b128 v[216:219], v154 offset:5120
	ds_read_b128 v[220:223], v154 offset:6144
	ds_read_b128 v[224:227], v154 offset:7168
	global_load_lds_dwordx4 v[196:197], off sc1
	v_lshl_add_u64 v[196:197], v[146:147], 0, s[64:65]
	s_mov_b32 m0, s41
	s_nop 0
	global_load_lds_dwordx4 v[196:197], off sc1
	s_waitcnt vmcnt(8)
	s_waitcnt lgkmcnt(0)
	s_barrier
	s_setprio 1
	s_waitcnt lgkmcnt(0)
	v_mfma_f32_16x16x32_bf16 v[112:115], v[156:159], v[192:195], v[112:115]
	v_mfma_f32_16x16x32_bf16 v[116:119], v[164:167], v[192:195], v[116:119]
	v_mfma_f32_16x16x32_bf16 v[96:99], v[156:159], v[204:207], v[96:99]
	v_mfma_f32_16x16x32_bf16 v[100:103], v[164:167], v[204:207], v[100:103]
	v_mfma_f32_16x16x32_bf16 v[80:83], v[156:159], v[212:215], v[80:83]
	v_mfma_f32_16x16x32_bf16 v[84:87], v[164:167], v[212:215], v[84:87]
	v_mfma_f32_16x16x32_bf16 v[64:67], v[156:159], v[220:223], v[64:67]
	v_mfma_f32_16x16x32_bf16 v[68:71], v[164:167], v[220:223], v[68:71]
	v_mfma_f32_16x16x32_bf16 v[112:115], v[160:163], v[200:203], v[112:115]
	v_mfma_f32_16x16x32_bf16 v[116:119], v[168:171], v[200:203], v[116:119]
	v_mfma_f32_16x16x32_bf16 v[96:99], v[160:163], v[208:211], v[96:99]
	v_mfma_f32_16x16x32_bf16 v[100:103], v[168:171], v[208:211], v[100:103]
	v_mfma_f32_16x16x32_bf16 v[80:83], v[160:163], v[216:219], v[80:83]
	v_mfma_f32_16x16x32_bf16 v[84:87], v[168:171], v[216:219], v[84:87]
	v_mfma_f32_16x16x32_bf16 v[64:67], v[160:163], v[224:227], v[64:67]
	v_mfma_f32_16x16x32_bf16 v[68:71], v[168:171], v[224:227], v[68:71]
	s_setprio 0
	s_setprio 1
	v_mfma_f32_16x16x32_bf16 v[120:123], v[172:175], v[192:195], v[120:123]
	v_mfma_f32_16x16x32_bf16 v[124:127], v[180:183], v[192:195], v[124:127]
	v_mfma_f32_16x16x32_bf16 v[104:107], v[172:175], v[204:207], v[104:107]
	v_mfma_f32_16x16x32_bf16 v[108:111], v[180:183], v[204:207], v[108:111]
	v_mfma_f32_16x16x32_bf16 v[88:91], v[172:175], v[212:215], v[88:91]
	v_mfma_f32_16x16x32_bf16 v[92:95], v[180:183], v[212:215], v[92:95]
	v_mfma_f32_16x16x32_bf16 v[72:75], v[172:175], v[220:223], v[72:75]
	v_mfma_f32_16x16x32_bf16 v[76:79], v[180:183], v[220:223], v[76:79]
	v_mfma_f32_16x16x32_bf16 v[120:123], v[176:179], v[200:203], v[120:123]
	v_mfma_f32_16x16x32_bf16 v[124:127], v[184:187], v[200:203], v[124:127]
	v_mfma_f32_16x16x32_bf16 v[104:107], v[176:179], v[208:211], v[104:107]
	v_mfma_f32_16x16x32_bf16 v[108:111], v[184:187], v[208:211], v[108:111]
	v_mfma_f32_16x16x32_bf16 v[88:91], v[176:179], v[216:219], v[88:91]
	v_mfma_f32_16x16x32_bf16 v[92:95], v[184:187], v[216:219], v[92:95]
	v_mfma_f32_16x16x32_bf16 v[72:75], v[176:179], v[224:227], v[72:75]
	v_mfma_f32_16x16x32_bf16 v[76:79], v[184:187], v[224:227], v[76:79]
	s_setprio 0
	s_barrier
	s_add_i32 s88, s49, s35
	s_mov_b32 m0, s88
	ds_read_b128 v[192:195], v154 offset:16384
	ds_read_b128 v[200:203], v154 offset:17408
	ds_read_b128 v[204:207], v154 offset:18432
	ds_read_b128 v[208:211], v154 offset:19456
	ds_read_b128 v[212:215], v154 offset:20480
	ds_read_b128 v[216:219], v154 offset:21504
	ds_read_b128 v[220:223], v154 offset:22528
	ds_read_b128 v[224:227], v154 offset:23552
	global_load_lds_dwordx4 v130, s[70:71] sc1
	s_add_i32 m0, s88, 0x2000
	s_add_u32 s88, s70, 0x4000
	s_addc_u32 s89, s71, 0
	s_add_i32 s90, s51, s35
	global_load_lds_dwordx4 v134, s[70:71] sc1
	s_mov_b32 m0, s90
	s_nop 0
	global_load_lds_dwordx4 v130, s[88:89] sc1
	s_add_i32 m0, s90, 0x2000
	s_nop 0
	global_load_lds_dwordx4 v134, s[88:89] sc1
	s_mov_b32 m0, s37
	s_nop 0
	global_load_lds_dwordx4 v128, s[78:79] sc1
	s_mov_b32 m0, s43
	s_nop 0
	global_load_lds_dwordx4 v132, s[78:79] sc1
	s_waitcnt vmcnt(8)
	s_waitcnt lgkmcnt(0)
	s_barrier
	s_setprio 1
	s_waitcnt lgkmcnt(0)
	v_mfma_f32_16x16x32_bf16 v[48:51], v[156:159], v[192:195], v[48:51]
	v_mfma_f32_16x16x32_bf16 v[52:55], v[164:167], v[192:195], v[52:55]
	v_mfma_f32_16x16x32_bf16 v[32:35], v[156:159], v[204:207], v[32:35]
	v_mfma_f32_16x16x32_bf16 v[36:39], v[164:167], v[204:207], v[36:39]
	v_mfma_f32_16x16x32_bf16 v[16:19], v[156:159], v[212:215], v[16:19]
	v_mfma_f32_16x16x32_bf16 v[20:23], v[164:167], v[212:215], v[20:23]
	v_mfma_f32_16x16x32_bf16 v[0:3], v[156:159], v[220:223], v[0:3]
	v_mfma_f32_16x16x32_bf16 v[4:7], v[164:167], v[220:223], v[4:7]
	v_mfma_f32_16x16x32_bf16 v[48:51], v[160:163], v[200:203], v[48:51]
	v_mfma_f32_16x16x32_bf16 v[52:55], v[168:171], v[200:203], v[52:55]
	v_mfma_f32_16x16x32_bf16 v[32:35], v[160:163], v[208:211], v[32:35]
	v_mfma_f32_16x16x32_bf16 v[36:39], v[168:171], v[208:211], v[36:39]
	v_mfma_f32_16x16x32_bf16 v[16:19], v[160:163], v[216:219], v[16:19]
	v_mfma_f32_16x16x32_bf16 v[20:23], v[168:171], v[216:219], v[20:23]
	v_mfma_f32_16x16x32_bf16 v[0:3], v[160:163], v[224:227], v[0:3]
	v_mfma_f32_16x16x32_bf16 v[4:7], v[168:171], v[224:227], v[4:7]
	s_setprio 0
	s_setprio 1
	v_mfma_f32_16x16x32_bf16 v[56:59], v[172:175], v[192:195], v[56:59]
	v_mfma_f32_16x16x32_bf16 v[60:63], v[180:183], v[192:195], v[60:63]
	v_mfma_f32_16x16x32_bf16 v[40:43], v[172:175], v[204:207], v[40:43]
	v_mfma_f32_16x16x32_bf16 v[44:47], v[180:183], v[204:207], v[44:47]
	v_mfma_f32_16x16x32_bf16 v[24:27], v[172:175], v[212:215], v[24:27]
	v_mfma_f32_16x16x32_bf16 v[28:31], v[180:183], v[212:215], v[28:31]
	v_mfma_f32_16x16x32_bf16 v[8:11], v[172:175], v[220:223], v[8:11]
	v_mfma_f32_16x16x32_bf16 v[12:15], v[180:183], v[220:223], v[12:15]
	v_mfma_f32_16x16x32_bf16 v[56:59], v[176:179], v[200:203], v[56:59]
	v_mfma_f32_16x16x32_bf16 v[60:63], v[184:187], v[200:203], v[60:63]
	v_mfma_f32_16x16x32_bf16 v[40:43], v[176:179], v[208:211], v[40:43]
	v_mfma_f32_16x16x32_bf16 v[44:47], v[184:187], v[208:211], v[44:47]
	v_mfma_f32_16x16x32_bf16 v[24:27], v[176:179], v[216:219], v[24:27]
	v_mfma_f32_16x16x32_bf16 v[28:31], v[184:187], v[216:219], v[28:31]
	v_mfma_f32_16x16x32_bf16 v[8:11], v[176:179], v[224:227], v[8:11]
	v_mfma_f32_16x16x32_bf16 v[12:15], v[184:187], v[224:227], v[12:15]
	s_setprio 0
	s_barrier
	v_add_u32_e32 v168, s54, v151
	v_add_u32_e32 v184, s55, v151
	ds_read_b128 v[156:159], v168
	ds_read_b128 v[160:163], v168 offset:1024
	ds_read_b128 v[164:167], v168 offset:2048
	ds_read_b128 v[168:171], v168 offset:3072
	ds_read_b128 v[172:175], v184
	ds_read_b128 v[176:179], v184 offset:1024
	ds_read_b128 v[180:183], v184 offset:2048
	ds_read_b128 v[184:187], v184 offset:3072
	s_add_u32 s78, s78, 0x4000
	s_addc_u32 s79, s79, 0
	s_mov_b32 m0, s44
	ds_read_b128 v[192:195], v154 offset:32768
	ds_read_b128 v[200:203], v154 offset:33792
	ds_read_b128 v[204:207], v154 offset:34816
	ds_read_b128 v[208:211], v154 offset:35840
	ds_read_b128 v[212:215], v154 offset:36864
	ds_read_b128 v[216:219], v154 offset:37888
	ds_read_b128 v[220:223], v154 offset:38912
	ds_read_b128 v[224:227], v154 offset:39936
	global_load_lds_dwordx4 v128, s[78:79] sc1
	s_mov_b32 m0, s45
	s_nop 0
	global_load_lds_dwordx4 v132, s[78:79] sc1
	s_waitcnt vmcnt(8)
	s_waitcnt lgkmcnt(0)
	s_barrier
	s_setprio 1
	s_waitcnt lgkmcnt(0)
	v_mfma_f32_16x16x32_bf16 v[112:115], v[156:159], v[192:195], v[112:115]
	v_mfma_f32_16x16x32_bf16 v[116:119], v[164:167], v[192:195], v[116:119]
	v_mfma_f32_16x16x32_bf16 v[96:99], v[156:159], v[204:207], v[96:99]
	v_mfma_f32_16x16x32_bf16 v[100:103], v[164:167], v[204:207], v[100:103]
	v_mfma_f32_16x16x32_bf16 v[80:83], v[156:159], v[212:215], v[80:83]
	v_mfma_f32_16x16x32_bf16 v[84:87], v[164:167], v[212:215], v[84:87]
	v_mfma_f32_16x16x32_bf16 v[64:67], v[156:159], v[220:223], v[64:67]
	v_mfma_f32_16x16x32_bf16 v[68:71], v[164:167], v[220:223], v[68:71]
	v_mfma_f32_16x16x32_bf16 v[112:115], v[160:163], v[200:203], v[112:115]
	v_mfma_f32_16x16x32_bf16 v[116:119], v[168:171], v[200:203], v[116:119]
	v_mfma_f32_16x16x32_bf16 v[96:99], v[160:163], v[208:211], v[96:99]
	v_mfma_f32_16x16x32_bf16 v[100:103], v[168:171], v[208:211], v[100:103]
	v_mfma_f32_16x16x32_bf16 v[80:83], v[160:163], v[216:219], v[80:83]
	v_mfma_f32_16x16x32_bf16 v[84:87], v[168:171], v[216:219], v[84:87]
	v_mfma_f32_16x16x32_bf16 v[64:67], v[160:163], v[224:227], v[64:67]
	v_mfma_f32_16x16x32_bf16 v[68:71], v[168:171], v[224:227], v[68:71]
	s_setprio 0
	s_setprio 1
	v_mfma_f32_16x16x32_bf16 v[120:123], v[172:175], v[192:195], v[120:123]
	v_mfma_f32_16x16x32_bf16 v[124:127], v[180:183], v[192:195], v[124:127]
	v_mfma_f32_16x16x32_bf16 v[104:107], v[172:175], v[204:207], v[104:107]
	v_mfma_f32_16x16x32_bf16 v[108:111], v[180:183], v[204:207], v[108:111]
	v_mfma_f32_16x16x32_bf16 v[88:91], v[172:175], v[212:215], v[88:91]
	v_mfma_f32_16x16x32_bf16 v[92:95], v[180:183], v[212:215], v[92:95]
	v_mfma_f32_16x16x32_bf16 v[72:75], v[172:175], v[220:223], v[72:75]
	v_mfma_f32_16x16x32_bf16 v[76:79], v[180:183], v[220:223], v[76:79]
	v_mfma_f32_16x16x32_bf16 v[120:123], v[176:179], v[200:203], v[120:123]
	v_mfma_f32_16x16x32_bf16 v[124:127], v[184:187], v[200:203], v[124:127]
	v_mfma_f32_16x16x32_bf16 v[104:107], v[176:179], v[208:211], v[104:107]
	v_mfma_f32_16x16x32_bf16 v[108:111], v[184:187], v[208:211], v[108:111]
	v_mfma_f32_16x16x32_bf16 v[88:91], v[176:179], v[216:219], v[88:91]
	v_mfma_f32_16x16x32_bf16 v[92:95], v[184:187], v[216:219], v[92:95]
	v_mfma_f32_16x16x32_bf16 v[72:75], v[176:179], v[224:227], v[72:75]
	v_mfma_f32_16x16x32_bf16 v[76:79], v[184:187], v[224:227], v[76:79]
	s_setprio 0
	s_barrier
	s_add_u32 s78, s70, 0x8000
	s_addc_u32 s79, s71, 0
	s_add_i32 s88, s54, s35
	s_mov_b32 m0, s88
	ds_read_b128 v[192:195], v154 offset:49152
	ds_read_b128 v[200:203], v154 offset:50176
	ds_read_b128 v[204:207], v154 offset:51200
	ds_read_b128 v[208:211], v154 offset:52224
	ds_read_b128 v[212:215], v154 offset:53248
	ds_read_b128 v[216:219], v154 offset:54272
	ds_read_b128 v[220:223], v154 offset:55296
	ds_read_b128 v[224:227], v154 offset:56320
	global_load_lds_dwordx4 v130, s[78:79] sc1
	s_add_i32 m0, s88, 0x2000
	s_add_u32 s70, s70, 0xc000
	global_load_lds_dwordx4 v134, s[78:79] sc1
	s_addc_u32 s71, s71, 0
	s_add_i32 s78, s55, s35
	s_mov_b32 m0, s78
	s_nop 0
	global_load_lds_dwordx4 v130, s[70:71] sc1
	s_add_i32 m0, s78, 0x2000
	s_nop 0
	global_load_lds_dwordx4 v134, s[70:71] sc1
	s_mov_b32 m0, s47
	s_nop 0
	global_load_lds_dwordx4 v128, s[66:67] sc1
	s_mov_b32 m0, s48
	s_nop 0
	global_load_lds_dwordx4 v132, s[66:67] sc1
	s_waitcnt vmcnt(8)
	s_waitcnt lgkmcnt(0)
	s_barrier
	s_setprio 1
	s_waitcnt lgkmcnt(0)
	v_mfma_f32_16x16x32_bf16 v[48:51], v[156:159], v[192:195], v[48:51]
	v_mfma_f32_16x16x32_bf16 v[52:55], v[164:167], v[192:195], v[52:55]
	v_mfma_f32_16x16x32_bf16 v[32:35], v[156:159], v[204:207], v[32:35]
	v_mfma_f32_16x16x32_bf16 v[36:39], v[164:167], v[204:207], v[36:39]
	v_mfma_f32_16x16x32_bf16 v[16:19], v[156:159], v[212:215], v[16:19]
	v_mfma_f32_16x16x32_bf16 v[20:23], v[164:167], v[212:215], v[20:23]
	v_mfma_f32_16x16x32_bf16 v[0:3], v[156:159], v[220:223], v[0:3]
	v_mfma_f32_16x16x32_bf16 v[4:7], v[164:167], v[220:223], v[4:7]
	v_mfma_f32_16x16x32_bf16 v[48:51], v[160:163], v[200:203], v[48:51]
	v_mfma_f32_16x16x32_bf16 v[52:55], v[168:171], v[200:203], v[52:55]
	v_mfma_f32_16x16x32_bf16 v[32:35], v[160:163], v[208:211], v[32:35]
	v_mfma_f32_16x16x32_bf16 v[36:39], v[168:171], v[208:211], v[36:39]
	v_mfma_f32_16x16x32_bf16 v[16:19], v[160:163], v[216:219], v[16:19]
	v_mfma_f32_16x16x32_bf16 v[20:23], v[168:171], v[216:219], v[20:23]
	v_mfma_f32_16x16x32_bf16 v[0:3], v[160:163], v[224:227], v[0:3]
	v_mfma_f32_16x16x32_bf16 v[4:7], v[168:171], v[224:227], v[4:7]
	s_setprio 0
	s_setprio 1
	v_mfma_f32_16x16x32_bf16 v[56:59], v[172:175], v[192:195], v[56:59]
	v_mfma_f32_16x16x32_bf16 v[60:63], v[180:183], v[192:195], v[60:63]
	v_mfma_f32_16x16x32_bf16 v[40:43], v[172:175], v[204:207], v[40:43]
	v_mfma_f32_16x16x32_bf16 v[44:47], v[180:183], v[204:207], v[44:47]
	v_mfma_f32_16x16x32_bf16 v[24:27], v[172:175], v[212:215], v[24:27]
	v_mfma_f32_16x16x32_bf16 v[28:31], v[180:183], v[212:215], v[28:31]
	v_mfma_f32_16x16x32_bf16 v[8:11], v[172:175], v[220:223], v[8:11]
	v_mfma_f32_16x16x32_bf16 v[12:15], v[180:183], v[220:223], v[12:15]
	v_mfma_f32_16x16x32_bf16 v[56:59], v[176:179], v[200:203], v[56:59]
	v_mfma_f32_16x16x32_bf16 v[60:63], v[184:187], v[200:203], v[60:63]
	v_mfma_f32_16x16x32_bf16 v[40:43], v[176:179], v[208:211], v[40:43]
	v_mfma_f32_16x16x32_bf16 v[44:47], v[184:187], v[208:211], v[44:47]
	v_mfma_f32_16x16x32_bf16 v[24:27], v[176:179], v[216:219], v[24:27]
	v_mfma_f32_16x16x32_bf16 v[28:31], v[184:187], v[216:219], v[28:31]
	v_mfma_f32_16x16x32_bf16 v[8:11], v[176:179], v[224:227], v[8:11]
	v_mfma_f32_16x16x32_bf16 v[12:15], v[184:187], v[224:227], v[12:15]
	s_setprio 0
	s_barrier
	s_add_i32 s87, s87, 2
	s_add_u32 s64, s64, 0x10000
	s_addc_u32 s65, s65, 0
	s_cmp_gt_u32 s87, 13
	s_cbranch_scc0 .LBB0_884
	s_add_u32 s64, s69, 0xffff0000
	s_addc_u32 s65, s80, -1
	s_andn2_b64 vcc, exec, s[8:9]
	s_cbranch_vccz .LBB0_876
	s_mov_b64 s[30:31], s[64:65]
	s_andn2_b64 vcc, exec, s[6:7]
	s_cbranch_vccnz .LBB0_877

.LBB0_976:
	s_add_u32 s66, s18, s64
	v_add_u32_e32 v151, s48, v149
	s_addc_u32 s67, s19, s65
	ds_read_b128 v[152:155], v151
	ds_read_b128 v[156:159], v151 offset:1024
	ds_read_b128 v[160:163], v151 offset:2048
	ds_read_b128 v[164:167], v151 offset:3072
	v_add_u32_e32 v151, s49, v149
	s_add_u32 s66, s66, 0x10000
	ds_read_b128 v[168:171], v151
	ds_read_b128 v[172:175], v151 offset:1024
	ds_read_b128 v[176:179], v151 offset:2048
	ds_read_b128 v[180:183], v151 offset:3072
	s_addc_u32 s67, s67, 0
	s_add_u32 s70, s55, s64
	s_addc_u32 s71, s69, s65
	s_cmp_eq_u32 s64, 0x70000
	s_cselect_b32 s78, s80, s66
	s_cselect_b32 s79, s41, s67
	s_cselect_b32 s70, s81, s70
	s_cselect_b32 s71, s39, s71
	s_add_u32 s66, s78, 0x8000
	s_addc_u32 s67, s79, 0
	v_lshl_add_u64 v[196:197], v[144:145], 0, s[64:65]
	s_add_i32 m0, s11, 0xc000
	ds_read_b128 v[184:187], v150
	ds_read_b128 v[192:195], v150 offset:1024
	ds_read_b128 v[200:203], v150 offset:2048
	ds_read_b128 v[204:207], v150 offset:3072
	ds_read_b128 v[208:211], v150 offset:4096
	ds_read_b128 v[212:215], v150 offset:5120
	ds_read_b128 v[216:219], v150 offset:6144
	ds_read_b128 v[220:223], v150 offset:7168
	global_load_lds_dwordx4 v[196:197], off sc1
	v_lshl_add_u64 v[196:197], v[146:147], 0, s[64:65]
	s_add_i32 m0, s11, 0xe000
	s_nop 0
	global_load_lds_dwordx4 v[196:197], off sc1
	s_waitcnt vmcnt(8)
	s_waitcnt lgkmcnt(0)
	s_barrier
	s_setprio 1
	s_waitcnt lgkmcnt(0)
	v_mfma_f32_16x16x32_bf16 v[104:107], v[152:155], v[184:187], v[104:107]
	v_mfma_f32_16x16x32_bf16 v[108:111], v[160:163], v[184:187], v[108:111]
	v_mfma_f32_16x16x32_bf16 v[84:87], v[152:155], v[200:203], v[84:87]
	v_mfma_f32_16x16x32_bf16 v[92:95], v[160:163], v[200:203], v[92:95]
	v_mfma_f32_16x16x32_bf16 v[72:75], v[152:155], v[208:211], v[72:75]
	v_mfma_f32_16x16x32_bf16 v[76:79], v[160:163], v[208:211], v[76:79]
	v_mfma_f32_16x16x32_bf16 v[64:67], v[152:155], v[216:219], v[64:67]
	v_mfma_f32_16x16x32_bf16 v[68:71], v[160:163], v[216:219], v[68:71]
	v_mfma_f32_16x16x32_bf16 v[104:107], v[156:159], v[192:195], v[104:107]
	v_mfma_f32_16x16x32_bf16 v[108:111], v[164:167], v[192:195], v[108:111]
	v_mfma_f32_16x16x32_bf16 v[84:87], v[156:159], v[204:207], v[84:87]
	v_mfma_f32_16x16x32_bf16 v[92:95], v[164:167], v[204:207], v[92:95]
	v_mfma_f32_16x16x32_bf16 v[72:75], v[156:159], v[212:215], v[72:75]
	v_mfma_f32_16x16x32_bf16 v[76:79], v[164:167], v[212:215], v[76:79]
	v_mfma_f32_16x16x32_bf16 v[64:67], v[156:159], v[220:223], v[64:67]
	v_mfma_f32_16x16x32_bf16 v[68:71], v[164:167], v[220:223], v[68:71]
	s_setprio 0
	s_setprio 1
	v_mfma_f32_16x16x32_bf16 v[120:123], v[168:171], v[184:187], v[120:123]
	v_mfma_f32_16x16x32_bf16 v[124:127], v[176:179], v[184:187], v[124:127]
	v_mfma_f32_16x16x32_bf16 v[112:115], v[168:171], v[200:203], v[112:115]
	v_mfma_f32_16x16x32_bf16 v[116:119], v[176:179], v[200:203], v[116:119]
	v_mfma_f32_16x16x32_bf16 v[96:99], v[168:171], v[208:211], v[96:99]
	v_mfma_f32_16x16x32_bf16 v[100:103], v[176:179], v[208:211], v[100:103]
	v_mfma_f32_16x16x32_bf16 v[80:83], v[168:171], v[216:219], v[80:83]
	v_mfma_f32_16x16x32_bf16 v[88:91], v[176:179], v[216:219], v[88:91]
	v_mfma_f32_16x16x32_bf16 v[120:123], v[172:175], v[192:195], v[120:123]
	v_mfma_f32_16x16x32_bf16 v[124:127], v[180:183], v[192:195], v[124:127]
	v_mfma_f32_16x16x32_bf16 v[112:115], v[172:175], v[204:207], v[112:115]
	v_mfma_f32_16x16x32_bf16 v[116:119], v[180:183], v[204:207], v[116:119]
	v_mfma_f32_16x16x32_bf16 v[96:99], v[172:175], v[212:215], v[96:99]
	v_mfma_f32_16x16x32_bf16 v[100:103], v[180:183], v[212:215], v[100:103]
	v_mfma_f32_16x16x32_bf16 v[80:83], v[172:175], v[220:223], v[80:83]
	v_mfma_f32_16x16x32_bf16 v[88:91], v[180:183], v[220:223], v[88:91]
	s_setprio 0
	s_barrier
	s_add_i32 s86, s48, s37
	s_mov_b32 m0, s86
	ds_read_b128 v[184:187], v150 offset:16384
	ds_read_b128 v[192:195], v150 offset:17408
	ds_read_b128 v[200:203], v150 offset:18432
	ds_read_b128 v[204:207], v150 offset:19456
	ds_read_b128 v[208:211], v150 offset:20480
	ds_read_b128 v[212:215], v150 offset:21504
	ds_read_b128 v[216:219], v150 offset:22528
	ds_read_b128 v[220:223], v150 offset:23552
	global_load_lds_dwordx4 v132, s[70:71] sc1
	s_add_i32 m0, s86, 0x2000
	s_add_u32 s86, s70, 0x4000
	s_addc_u32 s87, s71, 0
	s_add_i32 s88, s49, s37
	global_load_lds_dwordx4 v134, s[70:71] sc1
	s_mov_b32 m0, s88
	s_nop 0
	global_load_lds_dwordx4 v132, s[86:87] sc1
	s_add_i32 m0, s88, 0x2000
	s_nop 0
	global_load_lds_dwordx4 v134, s[86:87] sc1
	s_mov_b32 m0, s11
	s_nop 0
	global_load_lds_dwordx4 v128, s[78:79] sc1
	s_mov_b32 m0, s42
	s_nop 0
	global_load_lds_dwordx4 v130, s[78:79] sc1
	s_waitcnt vmcnt(8)
	s_waitcnt lgkmcnt(0)
	s_barrier
	s_setprio 1
	s_waitcnt lgkmcnt(0)
	v_mfma_f32_16x16x32_bf16 v[36:39], v[152:155], v[184:187], v[36:39]
	v_mfma_f32_16x16x32_bf16 v[44:47], v[160:163], v[184:187], v[44:47]
	v_mfma_f32_16x16x32_bf16 v[20:23], v[152:155], v[200:203], v[20:23]
	v_mfma_f32_16x16x32_bf16 v[28:31], v[160:163], v[200:203], v[28:31]
	v_mfma_f32_16x16x32_bf16 v[8:11], v[152:155], v[208:211], v[8:11]
	v_mfma_f32_16x16x32_bf16 v[12:15], v[160:163], v[208:211], v[12:15]
	v_mfma_f32_16x16x32_bf16 v[0:3], v[152:155], v[216:219], v[0:3]
	v_mfma_f32_16x16x32_bf16 v[4:7], v[160:163], v[216:219], v[4:7]
	v_mfma_f32_16x16x32_bf16 v[36:39], v[156:159], v[192:195], v[36:39]
	v_mfma_f32_16x16x32_bf16 v[44:47], v[164:167], v[192:195], v[44:47]
	v_mfma_f32_16x16x32_bf16 v[20:23], v[156:159], v[204:207], v[20:23]
	v_mfma_f32_16x16x32_bf16 v[28:31], v[164:167], v[204:207], v[28:31]
	v_mfma_f32_16x16x32_bf16 v[8:11], v[156:159], v[212:215], v[8:11]
	v_mfma_f32_16x16x32_bf16 v[12:15], v[164:167], v[212:215], v[12:15]
	v_mfma_f32_16x16x32_bf16 v[0:3], v[156:159], v[220:223], v[0:3]
	v_mfma_f32_16x16x32_bf16 v[4:7], v[164:167], v[220:223], v[4:7]
	s_setprio 0
	s_setprio 1
	v_mfma_f32_16x16x32_bf16 v[56:59], v[168:171], v[184:187], v[56:59]
	v_mfma_f32_16x16x32_bf16 v[60:63], v[176:179], v[184:187], v[60:63]
	v_mfma_f32_16x16x32_bf16 v[48:51], v[168:171], v[200:203], v[48:51]
	v_mfma_f32_16x16x32_bf16 v[52:55], v[176:179], v[200:203], v[52:55]
	v_mfma_f32_16x16x32_bf16 v[32:35], v[168:171], v[208:211], v[32:35]
	v_mfma_f32_16x16x32_bf16 v[40:43], v[176:179], v[208:211], v[40:43]
	v_mfma_f32_16x16x32_bf16 v[16:19], v[168:171], v[216:219], v[16:19]
	v_mfma_f32_16x16x32_bf16 v[24:27], v[176:179], v[216:219], v[24:27]
	v_mfma_f32_16x16x32_bf16 v[56:59], v[172:175], v[192:195], v[56:59]
	v_mfma_f32_16x16x32_bf16 v[60:63], v[180:183], v[192:195], v[60:63]
	v_mfma_f32_16x16x32_bf16 v[48:51], v[172:175], v[204:207], v[48:51]
	v_mfma_f32_16x16x32_bf16 v[52:55], v[180:183], v[204:207], v[52:55]
	v_mfma_f32_16x16x32_bf16 v[32:35], v[172:175], v[212:215], v[32:35]
	v_mfma_f32_16x16x32_bf16 v[40:43], v[180:183], v[212:215], v[40:43]
	v_mfma_f32_16x16x32_bf16 v[16:19], v[172:175], v[220:223], v[16:19]
	v_mfma_f32_16x16x32_bf16 v[24:27], v[180:183], v[220:223], v[24:27]
	s_setprio 0
	s_barrier
	v_add_u32_e32 v151, s50, v149
	ds_read_b128 v[152:155], v151
	ds_read_b128 v[156:159], v151 offset:1024
	ds_read_b128 v[160:163], v151 offset:2048
	ds_read_b128 v[164:167], v151 offset:3072
	v_add_u32_e32 v151, s51, v149
	ds_read_b128 v[168:171], v151
	ds_read_b128 v[172:175], v151 offset:1024
	ds_read_b128 v[176:179], v151 offset:2048
	ds_read_b128 v[180:183], v151 offset:3072
	s_add_u32 s78, s78, 0x4000
	s_addc_u32 s79, s79, 0
	s_mov_b32 m0, s43
	ds_read_b128 v[184:187], v150 offset:32768
	ds_read_b128 v[192:195], v150 offset:33792
	ds_read_b128 v[200:203], v150 offset:34816
	ds_read_b128 v[204:207], v150 offset:35840
	ds_read_b128 v[208:211], v150 offset:36864
	ds_read_b128 v[212:215], v150 offset:37888
	ds_read_b128 v[216:219], v150 offset:38912
	ds_read_b128 v[220:223], v150 offset:39936
	global_load_lds_dwordx4 v128, s[78:79] sc1
	s_mov_b32 m0, s44
	s_nop 0
	global_load_lds_dwordx4 v130, s[78:79] sc1
	s_waitcnt vmcnt(8)
	s_waitcnt lgkmcnt(0)
	s_barrier
	s_setprio 1
	s_waitcnt lgkmcnt(0)
	v_mfma_f32_16x16x32_bf16 v[104:107], v[152:155], v[184:187], v[104:107]
	v_mfma_f32_16x16x32_bf16 v[108:111], v[160:163], v[184:187], v[108:111]
	v_mfma_f32_16x16x32_bf16 v[84:87], v[152:155], v[200:203], v[84:87]
	v_mfma_f32_16x16x32_bf16 v[92:95], v[160:163], v[200:203], v[92:95]
	v_mfma_f32_16x16x32_bf16 v[72:75], v[152:155], v[208:211], v[72:75]
	v_mfma_f32_16x16x32_bf16 v[76:79], v[160:163], v[208:211], v[76:79]
	v_mfma_f32_16x16x32_bf16 v[64:67], v[152:155], v[216:219], v[64:67]
	v_mfma_f32_16x16x32_bf16 v[68:71], v[160:163], v[216:219], v[68:71]
	v_mfma_f32_16x16x32_bf16 v[104:107], v[156:159], v[192:195], v[104:107]
	v_mfma_f32_16x16x32_bf16 v[108:111], v[164:167], v[192:195], v[108:111]
	v_mfma_f32_16x16x32_bf16 v[84:87], v[156:159], v[204:207], v[84:87]
	v_mfma_f32_16x16x32_bf16 v[92:95], v[164:167], v[204:207], v[92:95]
	v_mfma_f32_16x16x32_bf16 v[72:75], v[156:159], v[212:215], v[72:75]
	v_mfma_f32_16x16x32_bf16 v[76:79], v[164:167], v[212:215], v[76:79]
	v_mfma_f32_16x16x32_bf16 v[64:67], v[156:159], v[220:223], v[64:67]
	v_mfma_f32_16x16x32_bf16 v[68:71], v[164:167], v[220:223], v[68:71]
	s_setprio 0
	s_setprio 1
	v_mfma_f32_16x16x32_bf16 v[120:123], v[168:171], v[184:187], v[120:123]
	v_mfma_f32_16x16x32_bf16 v[124:127], v[176:179], v[184:187], v[124:127]
	v_mfma_f32_16x16x32_bf16 v[112:115], v[168:171], v[200:203], v[112:115]
	v_mfma_f32_16x16x32_bf16 v[116:119], v[176:179], v[200:203], v[116:119]
	v_mfma_f32_16x16x32_bf16 v[96:99], v[168:171], v[208:211], v[96:99]
	v_mfma_f32_16x16x32_bf16 v[100:103], v[176:179], v[208:211], v[100:103]
	v_mfma_f32_16x16x32_bf16 v[80:83], v[168:171], v[216:219], v[80:83]
	v_mfma_f32_16x16x32_bf16 v[88:91], v[176:179], v[216:219], v[88:91]
	v_mfma_f32_16x16x32_bf16 v[120:123], v[172:175], v[192:195], v[120:123]
	v_mfma_f32_16x16x32_bf16 v[124:127], v[180:183], v[192:195], v[124:127]
	v_mfma_f32_16x16x32_bf16 v[112:115], v[172:175], v[204:207], v[112:115]
	v_mfma_f32_16x16x32_bf16 v[116:119], v[180:183], v[204:207], v[116:119]
	v_mfma_f32_16x16x32_bf16 v[96:99], v[172:175], v[212:215], v[96:99]
	v_mfma_f32_16x16x32_bf16 v[100:103], v[180:183], v[212:215], v[100:103]
	v_mfma_f32_16x16x32_bf16 v[80:83], v[172:175], v[220:223], v[80:83]
	v_mfma_f32_16x16x32_bf16 v[88:91], v[180:183], v[220:223], v[88:91]
	s_setprio 0
	s_barrier
	s_add_u32 s78, s70, 0x8000
	s_addc_u32 s79, s71, 0
	s_add_i32 s86, s50, s37
	s_mov_b32 m0, s86
	ds_read_b128 v[184:187], v150 offset:49152
	ds_read_b128 v[192:195], v150 offset:50176
	ds_read_b128 v[200:203], v150 offset:51200
	ds_read_b128 v[204:207], v150 offset:52224
	ds_read_b128 v[208:211], v150 offset:53248
	ds_read_b128 v[212:215], v150 offset:54272
	ds_read_b128 v[216:219], v150 offset:55296
	ds_read_b128 v[220:223], v150 offset:56320
	global_load_lds_dwordx4 v132, s[78:79] sc1
	s_add_i32 m0, s86, 0x2000
	s_add_u32 s70, s70, 0xc000
	global_load_lds_dwordx4 v134, s[78:79] sc1
	s_addc_u32 s71, s71, 0
	s_add_i32 s78, s51, s37
	s_mov_b32 m0, s78
	s_nop 0
	global_load_lds_dwordx4 v132, s[70:71] sc1
	s_add_i32 m0, s78, 0x2000
	s_nop 0
	global_load_lds_dwordx4 v134, s[70:71] sc1
	s_mov_b32 m0, s17
	s_nop 0
	global_load_lds_dwordx4 v128, s[66:67] sc1
	s_mov_b32 m0, s46
	s_nop 0
	global_load_lds_dwordx4 v130, s[66:67] sc1
	s_waitcnt vmcnt(8)
	s_waitcnt lgkmcnt(0)
	s_barrier
	s_setprio 1
	s_waitcnt lgkmcnt(0)
	v_mfma_f32_16x16x32_bf16 v[36:39], v[152:155], v[184:187], v[36:39]
	v_mfma_f32_16x16x32_bf16 v[44:47], v[160:163], v[184:187], v[44:47]
	v_mfma_f32_16x16x32_bf16 v[20:23], v[152:155], v[200:203], v[20:23]
	v_mfma_f32_16x16x32_bf16 v[28:31], v[160:163], v[200:203], v[28:31]
	v_mfma_f32_16x16x32_bf16 v[8:11], v[152:155], v[208:211], v[8:11]
	v_mfma_f32_16x16x32_bf16 v[12:15], v[160:163], v[208:211], v[12:15]
	v_mfma_f32_16x16x32_bf16 v[0:3], v[152:155], v[216:219], v[0:3]
	v_mfma_f32_16x16x32_bf16 v[4:7], v[160:163], v[216:219], v[4:7]
	v_mfma_f32_16x16x32_bf16 v[36:39], v[156:159], v[192:195], v[36:39]
	v_mfma_f32_16x16x32_bf16 v[44:47], v[164:167], v[192:195], v[44:47]
	v_mfma_f32_16x16x32_bf16 v[20:23], v[156:159], v[204:207], v[20:23]
	v_mfma_f32_16x16x32_bf16 v[28:31], v[164:167], v[204:207], v[28:31]
	v_mfma_f32_16x16x32_bf16 v[8:11], v[156:159], v[212:215], v[8:11]
	v_mfma_f32_16x16x32_bf16 v[12:15], v[164:167], v[212:215], v[12:15]
	v_mfma_f32_16x16x32_bf16 v[0:3], v[156:159], v[220:223], v[0:3]
	v_mfma_f32_16x16x32_bf16 v[4:7], v[164:167], v[220:223], v[4:7]
	s_setprio 0
	s_setprio 1
	v_mfma_f32_16x16x32_bf16 v[56:59], v[168:171], v[184:187], v[56:59]
	v_mfma_f32_16x16x32_bf16 v[60:63], v[176:179], v[184:187], v[60:63]
	v_mfma_f32_16x16x32_bf16 v[48:51], v[168:171], v[200:203], v[48:51]
	v_mfma_f32_16x16x32_bf16 v[52:55], v[176:179], v[200:203], v[52:55]
	v_mfma_f32_16x16x32_bf16 v[32:35], v[168:171], v[208:211], v[32:35]
	v_mfma_f32_16x16x32_bf16 v[40:43], v[176:179], v[208:211], v[40:43]
	v_mfma_f32_16x16x32_bf16 v[16:19], v[168:171], v[216:219], v[16:19]
	v_mfma_f32_16x16x32_bf16 v[24:27], v[176:179], v[216:219], v[24:27]
	v_mfma_f32_16x16x32_bf16 v[56:59], v[172:175], v[192:195], v[56:59]
	v_mfma_f32_16x16x32_bf16 v[60:63], v[180:183], v[192:195], v[60:63]
	v_mfma_f32_16x16x32_bf16 v[48:51], v[172:175], v[204:207], v[48:51]
	v_mfma_f32_16x16x32_bf16 v[52:55], v[180:183], v[204:207], v[52:55]
	v_mfma_f32_16x16x32_bf16 v[32:35], v[172:175], v[212:215], v[32:35]
	v_mfma_f32_16x16x32_bf16 v[40:43], v[180:183], v[212:215], v[40:43]
	v_mfma_f32_16x16x32_bf16 v[16:19], v[172:175], v[220:223], v[16:19]
	v_mfma_f32_16x16x32_bf16 v[24:27], v[180:183], v[220:223], v[24:27]
	s_setprio 0
	s_barrier
	s_add_i32 s85, s85, 2
	s_add_u32 s64, s64, 0x10000
	s_addc_u32 s65, s65, 0
	s_cmp_gt_u32 s85, 13
	s_cbranch_scc0 .LBB0_976
	s_add_u32 s64, s55, 0xffff0000
	s_addc_u32 s65, s69, -1
	s_andn2_b64 vcc, exec, s[8:9]
	s_cbranch_vccnz .LBB0_967
	s_mov_b32 s16, s38
	s_mov_b32 s10, s40
	s_mov_b64 s[18:19], s[62:63]
	s_mov_b32 s47, s54
	v_mov_b64 v[104:105], 0
	v_mov_b64 v[106:107], 0
	v_mov_b64 v[108:109], 0
	v_mov_b64 v[110:111], 0
	v_mov_b64 v[84:85], 0
	v_mov_b64 v[86:87], 0
	v_mov_b64 v[92:93], 0
	v_mov_b64 v[94:95], 0
	v_mov_b64 v[72:73], 0
	v_mov_b64 v[74:75], 0
	v_mov_b64 v[76:77], 0
	v_mov_b64 v[78:79], 0
	v_mov_b64 v[64:65], 0
	v_mov_b64 v[66:67], 0
	v_mov_b64 v[68:69], 0
	v_mov_b64 v[70:71], 0
	v_mov_b64 v[120:121], 0
	v_mov_b64 v[122:123], 0
	v_mov_b64 v[124:125], 0
	v_mov_b64 v[126:127], 0
	v_mov_b64 v[112:113], 0
	v_mov_b64 v[114:115], 0
	v_mov_b64 v[116:117], 0
	v_mov_b64 v[118:119], 0
	v_mov_b64 v[96:97], 0
	v_mov_b64 v[98:99], 0
	v_mov_b64 v[100:101], 0
	v_mov_b64 v[102:103], 0
	v_mov_b64 v[80:81], 0
	v_mov_b64 v[82:83], 0
	v_mov_b64 v[88:89], 0
	v_mov_b64 v[90:91], 0
	v_mov_b64 v[36:37], 0
	v_mov_b64 v[38:39], 0
	v_mov_b64 v[44:45], 0
	v_mov_b64 v[46:47], 0
	v_mov_b64 v[20:21], 0
	v_mov_b64 v[22:23], 0
	v_mov_b64 v[28:29], 0
	v_mov_b64 v[30:31], 0
	v_mov_b64 v[8:9], 0
	v_mov_b64 v[10:11], 0
	v_mov_b64 v[12:13], 0
	v_mov_b64 v[14:15], 0
	v_mov_b64 v[0:1], 0
	v_mov_b64 v[2:3], 0
	v_mov_b64 v[4:5], 0
	v_mov_b64 v[6:7], 0
	v_mov_b64 v[56:57], 0
	v_mov_b64 v[58:59], 0
	v_mov_b64 v[60:61], 0
	v_mov_b64 v[62:63], 0
	v_mov_b64 v[48:49], 0
	v_mov_b64 v[50:51], 0
	v_mov_b64 v[52:53], 0
	v_mov_b64 v[54:55], 0
	v_mov_b64 v[32:33], 0
	v_mov_b64 v[34:35], 0
	v_mov_b64 v[40:41], 0
	v_mov_b64 v[42:43], 0
	v_mov_b64 v[16:17], 0
	v_mov_b64 v[18:19], 0
	v_mov_b64 v[24:25], 0
	v_mov_b64 v[26:27], 0
	s_andn2_b64 vcc, exec, s[6:7]
	s_cbranch_vccnz .LBB0_968

.LBB0_1029:
	s_add_u32 s41, s56, s10
	s_addc_u32 s65, s57, s11
	v_add_u32_e32 v168, s50, v151
	v_add_u32_e32 v184, s51, v151
	s_add_u32 s41, s41, 0x10000
	ds_read_b128 v[156:159], v168
	ds_read_b128 v[160:163], v168 offset:1024
	ds_read_b128 v[164:167], v168 offset:2048
	ds_read_b128 v[168:171], v168 offset:3072
	ds_read_b128 v[172:175], v184
	ds_read_b128 v[176:179], v184 offset:1024
	ds_read_b128 v[180:183], v184 offset:2048
	ds_read_b128 v[184:187], v184 offset:3072
	s_addc_u32 s65, s65, 0
	s_add_u32 s70, s77, s10
	s_addc_u32 s71, s82, s11
	s_cmp_eq_u32 s10, 0x70000
	s_cselect_b32 s80, s84, s41
	s_cselect_b32 s81, s83, s65
	s_cselect_b32 s78, s86, s70
	s_cselect_b32 s79, s85, s71
	s_add_u32 s70, s80, 0x8000
	s_addc_u32 s71, s81, 0
	s_add_i32 s41, s42, 0xc000
	v_lshl_add_u64 v[196:197], v[144:145], 0, s[10:11]
	s_mov_b32 m0, s41
	s_add_i32 s65, s42, 0xe000
	ds_read_b128 v[192:195], v154
	ds_read_b128 v[200:203], v154 offset:1024
	ds_read_b128 v[204:207], v154 offset:2048
	ds_read_b128 v[208:211], v154 offset:3072
	ds_read_b128 v[212:215], v154 offset:4096
	ds_read_b128 v[216:219], v154 offset:5120
	ds_read_b128 v[220:223], v154 offset:6144
	ds_read_b128 v[224:227], v154 offset:7168
	global_load_lds_dwordx4 v[196:197], off sc1
	v_lshl_add_u64 v[196:197], v[146:147], 0, s[10:11]
	s_mov_b32 m0, s65
	s_nop 0
	global_load_lds_dwordx4 v[196:197], off sc1
	s_waitcnt vmcnt(8)
	s_waitcnt lgkmcnt(0)
	s_barrier
	s_setprio 1
	s_waitcnt lgkmcnt(0)
	v_mfma_f32_16x16x32_bf16 v[112:115], v[156:159], v[192:195], v[112:115]
	v_mfma_f32_16x16x32_bf16 v[116:119], v[164:167], v[192:195], v[116:119]
	v_mfma_f32_16x16x32_bf16 v[96:99], v[156:159], v[204:207], v[96:99]
	v_mfma_f32_16x16x32_bf16 v[100:103], v[164:167], v[204:207], v[100:103]
	v_mfma_f32_16x16x32_bf16 v[80:83], v[156:159], v[212:215], v[80:83]
	v_mfma_f32_16x16x32_bf16 v[84:87], v[164:167], v[212:215], v[84:87]
	v_mfma_f32_16x16x32_bf16 v[64:67], v[156:159], v[220:223], v[64:67]
	v_mfma_f32_16x16x32_bf16 v[68:71], v[164:167], v[220:223], v[68:71]
	v_mfma_f32_16x16x32_bf16 v[112:115], v[160:163], v[200:203], v[112:115]
	v_mfma_f32_16x16x32_bf16 v[116:119], v[168:171], v[200:203], v[116:119]
	v_mfma_f32_16x16x32_bf16 v[96:99], v[160:163], v[208:211], v[96:99]
	v_mfma_f32_16x16x32_bf16 v[100:103], v[168:171], v[208:211], v[100:103]
	v_mfma_f32_16x16x32_bf16 v[80:83], v[160:163], v[216:219], v[80:83]
	v_mfma_f32_16x16x32_bf16 v[84:87], v[168:171], v[216:219], v[84:87]
	v_mfma_f32_16x16x32_bf16 v[64:67], v[160:163], v[224:227], v[64:67]
	v_mfma_f32_16x16x32_bf16 v[68:71], v[168:171], v[224:227], v[68:71]
	s_setprio 0
	s_setprio 1
	v_mfma_f32_16x16x32_bf16 v[120:123], v[172:175], v[192:195], v[120:123]
	v_mfma_f32_16x16x32_bf16 v[124:127], v[180:183], v[192:195], v[124:127]
	v_mfma_f32_16x16x32_bf16 v[104:107], v[172:175], v[204:207], v[104:107]
	v_mfma_f32_16x16x32_bf16 v[108:111], v[180:183], v[204:207], v[108:111]
	v_mfma_f32_16x16x32_bf16 v[88:91], v[172:175], v[212:215], v[88:91]
	v_mfma_f32_16x16x32_bf16 v[92:95], v[180:183], v[212:215], v[92:95]
	v_mfma_f32_16x16x32_bf16 v[72:75], v[172:175], v[220:223], v[72:75]
	v_mfma_f32_16x16x32_bf16 v[76:79], v[180:183], v[220:223], v[76:79]
	v_mfma_f32_16x16x32_bf16 v[120:123], v[176:179], v[200:203], v[120:123]
	v_mfma_f32_16x16x32_bf16 v[124:127], v[184:187], v[200:203], v[124:127]
	v_mfma_f32_16x16x32_bf16 v[104:107], v[176:179], v[208:211], v[104:107]
	v_mfma_f32_16x16x32_bf16 v[108:111], v[184:187], v[208:211], v[108:111]
	v_mfma_f32_16x16x32_bf16 v[88:91], v[176:179], v[216:219], v[88:91]
	v_mfma_f32_16x16x32_bf16 v[92:95], v[184:187], v[216:219], v[92:95]
	v_mfma_f32_16x16x32_bf16 v[72:75], v[176:179], v[224:227], v[72:75]
	v_mfma_f32_16x16x32_bf16 v[76:79], v[184:187], v[224:227], v[76:79]
	s_setprio 0
	s_barrier
	s_add_i32 s88, s50, s35
	s_mov_b32 m0, s88
	ds_read_b128 v[192:195], v154 offset:16384
	ds_read_b128 v[200:203], v154 offset:17408
	ds_read_b128 v[204:207], v154 offset:18432
	ds_read_b128 v[208:211], v154 offset:19456
	ds_read_b128 v[212:215], v154 offset:20480
	ds_read_b128 v[216:219], v154 offset:21504
	ds_read_b128 v[220:223], v154 offset:22528
	ds_read_b128 v[224:227], v154 offset:23552
	global_load_lds_dwordx4 v132, s[78:79] sc1
	s_add_i32 m0, s88, 0x2000
	s_add_u32 s88, s78, 0x4000
	s_addc_u32 s89, s79, 0
	s_add_i32 s90, s51, s35
	global_load_lds_dwordx4 v134, s[78:79] sc1
	s_mov_b32 m0, s90
	s_nop 0
	global_load_lds_dwordx4 v132, s[88:89] sc1
	s_add_i32 m0, s90, 0x2000
	s_nop 0
	global_load_lds_dwordx4 v134, s[88:89] sc1
	s_mov_b32 m0, s42
	s_nop 0
	global_load_lds_dwordx4 v128, s[80:81] sc1
	s_mov_b32 m0, s43
	s_nop 0
	global_load_lds_dwordx4 v130, s[80:81] sc1
	s_waitcnt vmcnt(8)
	s_waitcnt lgkmcnt(0)
	s_barrier
	s_setprio 1
	s_waitcnt lgkmcnt(0)
	v_mfma_f32_16x16x32_bf16 v[48:51], v[156:159], v[192:195], v[48:51]
	v_mfma_f32_16x16x32_bf16 v[52:55], v[164:167], v[192:195], v[52:55]
	v_mfma_f32_16x16x32_bf16 v[32:35], v[156:159], v[204:207], v[32:35]
	v_mfma_f32_16x16x32_bf16 v[36:39], v[164:167], v[204:207], v[36:39]
	v_mfma_f32_16x16x32_bf16 v[16:19], v[156:159], v[212:215], v[16:19]
	v_mfma_f32_16x16x32_bf16 v[20:23], v[164:167], v[212:215], v[20:23]
	v_mfma_f32_16x16x32_bf16 v[0:3], v[156:159], v[220:223], v[0:3]
	v_mfma_f32_16x16x32_bf16 v[4:7], v[164:167], v[220:223], v[4:7]
	v_mfma_f32_16x16x32_bf16 v[48:51], v[160:163], v[200:203], v[48:51]
	v_mfma_f32_16x16x32_bf16 v[52:55], v[168:171], v[200:203], v[52:55]
	v_mfma_f32_16x16x32_bf16 v[32:35], v[160:163], v[208:211], v[32:35]
	v_mfma_f32_16x16x32_bf16 v[36:39], v[168:171], v[208:211], v[36:39]
	v_mfma_f32_16x16x32_bf16 v[16:19], v[160:163], v[216:219], v[16:19]
	v_mfma_f32_16x16x32_bf16 v[20:23], v[168:171], v[216:219], v[20:23]
	v_mfma_f32_16x16x32_bf16 v[0:3], v[160:163], v[224:227], v[0:3]
	v_mfma_f32_16x16x32_bf16 v[4:7], v[168:171], v[224:227], v[4:7]
	s_setprio 0
	s_setprio 1
	v_mfma_f32_16x16x32_bf16 v[56:59], v[172:175], v[192:195], v[56:59]
	v_mfma_f32_16x16x32_bf16 v[60:63], v[180:183], v[192:195], v[60:63]
	v_mfma_f32_16x16x32_bf16 v[40:43], v[172:175], v[204:207], v[40:43]
	v_mfma_f32_16x16x32_bf16 v[44:47], v[180:183], v[204:207], v[44:47]
	v_mfma_f32_16x16x32_bf16 v[24:27], v[172:175], v[212:215], v[24:27]
	v_mfma_f32_16x16x32_bf16 v[28:31], v[180:183], v[212:215], v[28:31]
	v_mfma_f32_16x16x32_bf16 v[8:11], v[172:175], v[220:223], v[8:11]
	v_mfma_f32_16x16x32_bf16 v[12:15], v[180:183], v[220:223], v[12:15]
	v_mfma_f32_16x16x32_bf16 v[56:59], v[176:179], v[200:203], v[56:59]
	v_mfma_f32_16x16x32_bf16 v[60:63], v[184:187], v[200:203], v[60:63]
	v_mfma_f32_16x16x32_bf16 v[40:43], v[176:179], v[208:211], v[40:43]
	v_mfma_f32_16x16x32_bf16 v[44:47], v[184:187], v[208:211], v[44:47]
	v_mfma_f32_16x16x32_bf16 v[24:27], v[176:179], v[216:219], v[24:27]
	v_mfma_f32_16x16x32_bf16 v[28:31], v[184:187], v[216:219], v[28:31]
	v_mfma_f32_16x16x32_bf16 v[8:11], v[176:179], v[224:227], v[8:11]
	v_mfma_f32_16x16x32_bf16 v[12:15], v[184:187], v[224:227], v[12:15]
	s_setprio 0
	s_barrier
	v_add_u32_e32 v168, s54, v151
	v_add_u32_e32 v184, s55, v151
	ds_read_b128 v[156:159], v168
	ds_read_b128 v[160:163], v168 offset:1024
	ds_read_b128 v[164:167], v168 offset:2048
	ds_read_b128 v[168:171], v168 offset:3072
	ds_read_b128 v[172:175], v184
	ds_read_b128 v[176:179], v184 offset:1024
	ds_read_b128 v[180:183], v184 offset:2048
	ds_read_b128 v[184:187], v184 offset:3072
	s_add_u32 s80, s80, 0x4000
	s_addc_u32 s81, s81, 0
	s_mov_b32 m0, s44
	ds_read_b128 v[192:195], v154 offset:32768
	ds_read_b128 v[200:203], v154 offset:33792
	ds_read_b128 v[204:207], v154 offset:34816
	ds_read_b128 v[208:211], v154 offset:35840
	ds_read_b128 v[212:215], v154 offset:36864
	ds_read_b128 v[216:219], v154 offset:37888
	ds_read_b128 v[220:223], v154 offset:38912
	ds_read_b128 v[224:227], v154 offset:39936
	global_load_lds_dwordx4 v128, s[80:81] sc1
	s_mov_b32 m0, s45
	s_nop 0
	global_load_lds_dwordx4 v130, s[80:81] sc1
	s_waitcnt vmcnt(8)
	s_waitcnt lgkmcnt(0)
	s_barrier
	s_setprio 1
	s_waitcnt lgkmcnt(0)
	v_mfma_f32_16x16x32_bf16 v[112:115], v[156:159], v[192:195], v[112:115]
	v_mfma_f32_16x16x32_bf16 v[116:119], v[164:167], v[192:195], v[116:119]
	v_mfma_f32_16x16x32_bf16 v[96:99], v[156:159], v[204:207], v[96:99]
	v_mfma_f32_16x16x32_bf16 v[100:103], v[164:167], v[204:207], v[100:103]
	v_mfma_f32_16x16x32_bf16 v[80:83], v[156:159], v[212:215], v[80:83]
	v_mfma_f32_16x16x32_bf16 v[84:87], v[164:167], v[212:215], v[84:87]
	v_mfma_f32_16x16x32_bf16 v[64:67], v[156:159], v[220:223], v[64:67]
	v_mfma_f32_16x16x32_bf16 v[68:71], v[164:167], v[220:223], v[68:71]
	v_mfma_f32_16x16x32_bf16 v[112:115], v[160:163], v[200:203], v[112:115]
	v_mfma_f32_16x16x32_bf16 v[116:119], v[168:171], v[200:203], v[116:119]
	v_mfma_f32_16x16x32_bf16 v[96:99], v[160:163], v[208:211], v[96:99]
	v_mfma_f32_16x16x32_bf16 v[100:103], v[168:171], v[208:211], v[100:103]
	v_mfma_f32_16x16x32_bf16 v[80:83], v[160:163], v[216:219], v[80:83]
	v_mfma_f32_16x16x32_bf16 v[84:87], v[168:171], v[216:219], v[84:87]
	v_mfma_f32_16x16x32_bf16 v[64:67], v[160:163], v[224:227], v[64:67]
	v_mfma_f32_16x16x32_bf16 v[68:71], v[168:171], v[224:227], v[68:71]
	s_setprio 0
	s_setprio 1
	v_mfma_f32_16x16x32_bf16 v[120:123], v[172:175], v[192:195], v[120:123]
	v_mfma_f32_16x16x32_bf16 v[124:127], v[180:183], v[192:195], v[124:127]
	v_mfma_f32_16x16x32_bf16 v[104:107], v[172:175], v[204:207], v[104:107]
	v_mfma_f32_16x16x32_bf16 v[108:111], v[180:183], v[204:207], v[108:111]
	v_mfma_f32_16x16x32_bf16 v[88:91], v[172:175], v[212:215], v[88:91]
	v_mfma_f32_16x16x32_bf16 v[92:95], v[180:183], v[212:215], v[92:95]
	v_mfma_f32_16x16x32_bf16 v[72:75], v[172:175], v[220:223], v[72:75]
	v_mfma_f32_16x16x32_bf16 v[76:79], v[180:183], v[220:223], v[76:79]
	v_mfma_f32_16x16x32_bf16 v[120:123], v[176:179], v[200:203], v[120:123]
	v_mfma_f32_16x16x32_bf16 v[124:127], v[184:187], v[200:203], v[124:127]
	v_mfma_f32_16x16x32_bf16 v[104:107], v[176:179], v[208:211], v[104:107]
	v_mfma_f32_16x16x32_bf16 v[108:111], v[184:187], v[208:211], v[108:111]
	v_mfma_f32_16x16x32_bf16 v[88:91], v[176:179], v[216:219], v[88:91]
	v_mfma_f32_16x16x32_bf16 v[92:95], v[184:187], v[216:219], v[92:95]
	v_mfma_f32_16x16x32_bf16 v[72:75], v[176:179], v[224:227], v[72:75]
	v_mfma_f32_16x16x32_bf16 v[76:79], v[184:187], v[224:227], v[76:79]
	s_setprio 0
	s_barrier
	s_add_u32 s80, s78, 0x8000
	s_addc_u32 s81, s79, 0
	s_add_i32 s88, s54, s35
	s_mov_b32 m0, s88
	ds_read_b128 v[192:195], v154 offset:49152
	ds_read_b128 v[200:203], v154 offset:50176
	ds_read_b128 v[204:207], v154 offset:51200
	ds_read_b128 v[208:211], v154 offset:52224
	ds_read_b128 v[212:215], v154 offset:53248
	ds_read_b128 v[216:219], v154 offset:54272
	ds_read_b128 v[220:223], v154 offset:55296
	ds_read_b128 v[224:227], v154 offset:56320
	global_load_lds_dwordx4 v132, s[80:81] sc1
	s_add_i32 m0, s88, 0x2000
	s_add_u32 s78, s78, 0xc000
	global_load_lds_dwordx4 v134, s[80:81] sc1
	s_addc_u32 s79, s79, 0
	s_add_i32 s80, s55, s35
	s_mov_b32 m0, s80
	s_nop 0
	global_load_lds_dwordx4 v132, s[78:79] sc1
	s_add_i32 m0, s80, 0x2000
	s_nop 0
	global_load_lds_dwordx4 v134, s[78:79] sc1
	s_mov_b32 m0, s47
	s_nop 0
	global_load_lds_dwordx4 v128, s[70:71] sc1
	s_mov_b32 m0, s48
	s_nop 0
	global_load_lds_dwordx4 v130, s[70:71] sc1
	s_waitcnt vmcnt(8)
	s_waitcnt lgkmcnt(0)
	s_barrier
	s_setprio 1
	s_waitcnt lgkmcnt(0)
	v_mfma_f32_16x16x32_bf16 v[48:51], v[156:159], v[192:195], v[48:51]
	v_mfma_f32_16x16x32_bf16 v[52:55], v[164:167], v[192:195], v[52:55]
	v_mfma_f32_16x16x32_bf16 v[32:35], v[156:159], v[204:207], v[32:35]
	v_mfma_f32_16x16x32_bf16 v[36:39], v[164:167], v[204:207], v[36:39]
	v_mfma_f32_16x16x32_bf16 v[16:19], v[156:159], v[212:215], v[16:19]
	v_mfma_f32_16x16x32_bf16 v[20:23], v[164:167], v[212:215], v[20:23]
	v_mfma_f32_16x16x32_bf16 v[0:3], v[156:159], v[220:223], v[0:3]
	v_mfma_f32_16x16x32_bf16 v[4:7], v[164:167], v[220:223], v[4:7]
	v_mfma_f32_16x16x32_bf16 v[48:51], v[160:163], v[200:203], v[48:51]
	v_mfma_f32_16x16x32_bf16 v[52:55], v[168:171], v[200:203], v[52:55]
	v_mfma_f32_16x16x32_bf16 v[32:35], v[160:163], v[208:211], v[32:35]
	v_mfma_f32_16x16x32_bf16 v[36:39], v[168:171], v[208:211], v[36:39]
	v_mfma_f32_16x16x32_bf16 v[16:19], v[160:163], v[216:219], v[16:19]
	v_mfma_f32_16x16x32_bf16 v[20:23], v[168:171], v[216:219], v[20:23]
	v_mfma_f32_16x16x32_bf16 v[0:3], v[160:163], v[224:227], v[0:3]
	v_mfma_f32_16x16x32_bf16 v[4:7], v[168:171], v[224:227], v[4:7]
	s_setprio 0
	s_setprio 1
	v_mfma_f32_16x16x32_bf16 v[56:59], v[172:175], v[192:195], v[56:59]
	v_mfma_f32_16x16x32_bf16 v[60:63], v[180:183], v[192:195], v[60:63]
	v_mfma_f32_16x16x32_bf16 v[40:43], v[172:175], v[204:207], v[40:43]
	v_mfma_f32_16x16x32_bf16 v[44:47], v[180:183], v[204:207], v[44:47]
	v_mfma_f32_16x16x32_bf16 v[24:27], v[172:175], v[212:215], v[24:27]
	v_mfma_f32_16x16x32_bf16 v[28:31], v[180:183], v[212:215], v[28:31]
	v_mfma_f32_16x16x32_bf16 v[8:11], v[172:175], v[220:223], v[8:11]
	v_mfma_f32_16x16x32_bf16 v[12:15], v[180:183], v[220:223], v[12:15]
	v_mfma_f32_16x16x32_bf16 v[56:59], v[176:179], v[200:203], v[56:59]
	v_mfma_f32_16x16x32_bf16 v[60:63], v[184:187], v[200:203], v[60:63]
	v_mfma_f32_16x16x32_bf16 v[40:43], v[176:179], v[208:211], v[40:43]
	v_mfma_f32_16x16x32_bf16 v[44:47], v[184:187], v[208:211], v[44:47]
	v_mfma_f32_16x16x32_bf16 v[24:27], v[176:179], v[216:219], v[24:27]
	v_mfma_f32_16x16x32_bf16 v[28:31], v[184:187], v[216:219], v[28:31]
	v_mfma_f32_16x16x32_bf16 v[8:11], v[176:179], v[224:227], v[8:11]
	v_mfma_f32_16x16x32_bf16 v[12:15], v[184:187], v[224:227], v[12:15]
	s_setprio 0
	s_barrier
	s_add_i32 s87, s87, 2
	s_add_u32 s10, s10, 0x10000
	s_addc_u32 s11, s11, 0
	s_cmp_gt_u32 s87, 13
	s_cbranch_scc0 .LBB0_1029
	s_add_u32 s10, s77, 0xffff0000
	s_addc_u32 s11, s82, -1
	s_and_b64 vcc, exec, s[8:9]
	s_cbranch_vccz .LBB0_1019
	s_mov_b64 s[62:63], s[10:11]
	s_andn2_b64 vcc, exec, s[6:7]
	s_cbranch_vccnz .LBB0_1020

.LBB0_1093:
	v_add_u32_e32 v155, s47, v148
	ds_read_b128 v[156:159], v155
	ds_read_b128 v[160:163], v155 offset:1024
	ds_read_b128 v[164:167], v155 offset:2048
	ds_read_b128 v[168:171], v155 offset:3072
	v_add_u32_e32 v155, s48, v148
	ds_read_b128 v[172:175], v155
	ds_read_b128 v[176:179], v155 offset:1024
	ds_read_b128 v[180:183], v155 offset:2048
	ds_read_b128 v[184:187], v155 offset:3072
	s_add_u32 s40, s18, 0x10000
	s_addc_u32 s41, s19, 0
	s_cmp_eq_u32 s78, 12
	s_cselect_b32 s64, s69, s40
	s_cselect_b32 s65, s55, s41
	s_cselect_b32 s62, s71, s76
	s_cselect_b32 s63, s70, s77
	s_add_u32 s56, s64, 0x8000
	s_addc_u32 s57, s65, 0
	s_add_i32 m0, s37, 0xc000
	ds_read_b128 v[192:195], v154
	ds_read_b128 v[200:203], v154 offset:1024
	ds_read_b128 v[204:207], v154 offset:2048
	ds_read_b128 v[208:211], v154 offset:3072
	ds_read_b128 v[212:215], v154 offset:4096
	ds_read_b128 v[216:219], v154 offset:5120
	ds_read_b128 v[220:223], v154 offset:6144
	ds_read_b128 v[224:227], v154 offset:7168
	global_load_lds_dwordx4 v144, s[18:19] sc1
	s_add_i32 m0, s37, 0xe000
	s_nop 0
	global_load_lds_dwordx4 v146, s[18:19] sc1
	s_waitcnt vmcnt(8)
	s_waitcnt lgkmcnt(0)
	s_barrier
	s_setprio 1
	s_waitcnt lgkmcnt(0)
	v_mfma_f32_16x16x32_bf16 v[116:119], v[156:159], v[192:195], v[116:119]
	v_mfma_f32_16x16x32_bf16 v[108:111], v[164:167], v[192:195], v[108:111]
	v_mfma_f32_16x16x32_bf16 v[100:103], v[156:159], v[204:207], v[100:103]
	v_mfma_f32_16x16x32_bf16 v[92:95], v[164:167], v[204:207], v[92:95]
	v_mfma_f32_16x16x32_bf16 v[84:87], v[156:159], v[212:215], v[84:87]
	v_mfma_f32_16x16x32_bf16 v[76:79], v[164:167], v[212:215], v[76:79]
	v_mfma_f32_16x16x32_bf16 v[60:63], v[156:159], v[220:223], v[60:63]
	v_mfma_f32_16x16x32_bf16 v[52:55], v[164:167], v[220:223], v[52:55]
	v_mfma_f32_16x16x32_bf16 v[116:119], v[160:163], v[200:203], v[116:119]
	v_mfma_f32_16x16x32_bf16 v[108:111], v[168:171], v[200:203], v[108:111]
	v_mfma_f32_16x16x32_bf16 v[100:103], v[160:163], v[208:211], v[100:103]
	v_mfma_f32_16x16x32_bf16 v[92:95], v[168:171], v[208:211], v[92:95]
	v_mfma_f32_16x16x32_bf16 v[84:87], v[160:163], v[216:219], v[84:87]
	v_mfma_f32_16x16x32_bf16 v[76:79], v[168:171], v[216:219], v[76:79]
	v_mfma_f32_16x16x32_bf16 v[60:63], v[160:163], v[224:227], v[60:63]
	v_mfma_f32_16x16x32_bf16 v[52:55], v[168:171], v[224:227], v[52:55]
	s_setprio 0
	s_setprio 1
	v_mfma_f32_16x16x32_bf16 v[124:127], v[172:175], v[192:195], v[124:127]
	v_mfma_f32_16x16x32_bf16 v[120:123], v[180:183], v[192:195], v[120:123]
	v_mfma_f32_16x16x32_bf16 v[112:115], v[172:175], v[204:207], v[112:115]
	v_mfma_f32_16x16x32_bf16 v[104:107], v[180:183], v[204:207], v[104:107]
	v_mfma_f32_16x16x32_bf16 v[96:99], v[172:175], v[212:215], v[96:99]
	v_mfma_f32_16x16x32_bf16 v[88:91], v[180:183], v[212:215], v[88:91]
	v_mfma_f32_16x16x32_bf16 v[80:83], v[172:175], v[220:223], v[80:83]
	v_mfma_f32_16x16x32_bf16 v[68:71], v[180:183], v[220:223], v[68:71]
	v_mfma_f32_16x16x32_bf16 v[124:127], v[176:179], v[200:203], v[124:127]
	v_mfma_f32_16x16x32_bf16 v[120:123], v[184:187], v[200:203], v[120:123]
	v_mfma_f32_16x16x32_bf16 v[112:115], v[176:179], v[208:211], v[112:115]
	v_mfma_f32_16x16x32_bf16 v[104:107], v[184:187], v[208:211], v[104:107]
	v_mfma_f32_16x16x32_bf16 v[96:99], v[176:179], v[216:219], v[96:99]
	v_mfma_f32_16x16x32_bf16 v[88:91], v[184:187], v[216:219], v[88:91]
	v_mfma_f32_16x16x32_bf16 v[80:83], v[176:179], v[224:227], v[80:83]
	v_mfma_f32_16x16x32_bf16 v[68:71], v[184:187], v[224:227], v[68:71]
	s_setprio 0
	s_barrier
	s_add_i32 s18, s47, s36
	s_mov_b32 m0, s18
	ds_read_b128 v[192:195], v154 offset:16384
	ds_read_b128 v[200:203], v154 offset:17408
	ds_read_b128 v[204:207], v154 offset:18432
	ds_read_b128 v[208:211], v154 offset:19456
	ds_read_b128 v[212:215], v154 offset:20480
	ds_read_b128 v[216:219], v154 offset:21504
	ds_read_b128 v[220:223], v154 offset:22528
	ds_read_b128 v[224:227], v154 offset:23552
	global_load_lds_dwordx4 v132, s[62:63] sc1
	s_add_i32 m0, s18, 0x2000
	s_add_u32 s18, s62, 0x4000
	s_addc_u32 s19, s63, 0
	s_add_i32 s79, s48, s36
	global_load_lds_dwordx4 v134, s[62:63] sc1
	s_mov_b32 m0, s79
	s_nop 0
	global_load_lds_dwordx4 v132, s[18:19] sc1
	s_add_i32 m0, s79, 0x2000
	s_nop 0
	global_load_lds_dwordx4 v134, s[18:19] sc1
	s_mov_b32 m0, s37
	s_nop 0
	global_load_lds_dwordx4 v130, s[64:65] sc1
	s_mov_b32 m0, s42
	s_nop 0
	global_load_lds_dwordx4 v128, s[64:65] sc1
	s_waitcnt vmcnt(8)
	s_waitcnt lgkmcnt(0)
	s_barrier
	s_setprio 1
	s_waitcnt lgkmcnt(0)
	v_mfma_f32_16x16x32_bf16 v[56:59], v[156:159], v[192:195], v[56:59]
	v_mfma_f32_16x16x32_bf16 v[44:47], v[164:167], v[192:195], v[44:47]
	v_mfma_f32_16x16x32_bf16 v[36:39], v[156:159], v[204:207], v[36:39]
	v_mfma_f32_16x16x32_bf16 v[28:31], v[164:167], v[204:207], v[28:31]
	v_mfma_f32_16x16x32_bf16 v[20:23], v[156:159], v[212:215], v[20:23]
	v_mfma_f32_16x16x32_bf16 v[12:15], v[164:167], v[212:215], v[12:15]
	v_mfma_f32_16x16x32_bf16 v[4:7], v[156:159], v[220:223], v[4:7]
	v_mfma_f32_16x16x32_bf16 v[0:3], v[164:167], v[220:223], v[0:3]
	v_mfma_f32_16x16x32_bf16 v[56:59], v[160:163], v[200:203], v[56:59]
	v_mfma_f32_16x16x32_bf16 v[44:47], v[168:171], v[200:203], v[44:47]
	v_mfma_f32_16x16x32_bf16 v[36:39], v[160:163], v[208:211], v[36:39]
	v_mfma_f32_16x16x32_bf16 v[28:31], v[168:171], v[208:211], v[28:31]
	v_mfma_f32_16x16x32_bf16 v[20:23], v[160:163], v[216:219], v[20:23]
	v_mfma_f32_16x16x32_bf16 v[12:15], v[168:171], v[216:219], v[12:15]
	v_mfma_f32_16x16x32_bf16 v[4:7], v[160:163], v[224:227], v[4:7]
	v_mfma_f32_16x16x32_bf16 v[0:3], v[168:171], v[224:227], v[0:3]
	s_setprio 0
	s_setprio 1
	v_mfma_f32_16x16x32_bf16 v[72:75], v[172:175], v[192:195], v[72:75]
	v_mfma_f32_16x16x32_bf16 v[64:67], v[180:183], v[192:195], v[64:67]
	v_mfma_f32_16x16x32_bf16 v[48:51], v[172:175], v[204:207], v[48:51]
	v_mfma_f32_16x16x32_bf16 v[40:43], v[180:183], v[204:207], v[40:43]
	v_mfma_f32_16x16x32_bf16 v[32:35], v[172:175], v[212:215], v[32:35]
	v_mfma_f32_16x16x32_bf16 v[24:27], v[180:183], v[212:215], v[24:27]
	v_mfma_f32_16x16x32_bf16 v[16:19], v[172:175], v[220:223], v[16:19]
	v_mfma_f32_16x16x32_bf16 v[8:11], v[180:183], v[220:223], v[8:11]
	v_mfma_f32_16x16x32_bf16 v[72:75], v[176:179], v[200:203], v[72:75]
	v_mfma_f32_16x16x32_bf16 v[64:67], v[184:187], v[200:203], v[64:67]
	v_mfma_f32_16x16x32_bf16 v[48:51], v[176:179], v[208:211], v[48:51]
	v_mfma_f32_16x16x32_bf16 v[40:43], v[184:187], v[208:211], v[40:43]
	v_mfma_f32_16x16x32_bf16 v[32:35], v[176:179], v[216:219], v[32:35]
	v_mfma_f32_16x16x32_bf16 v[24:27], v[184:187], v[216:219], v[24:27]
	v_mfma_f32_16x16x32_bf16 v[16:19], v[176:179], v[224:227], v[16:19]
	v_mfma_f32_16x16x32_bf16 v[8:11], v[184:187], v[224:227], v[8:11]
	s_setprio 0
	s_barrier
	v_add_u32_e32 v155, s49, v148
	ds_read_b128 v[156:159], v155
	ds_read_b128 v[160:163], v155 offset:1024
	ds_read_b128 v[164:167], v155 offset:2048
	ds_read_b128 v[168:171], v155 offset:3072
	v_add_u32_e32 v155, s50, v148
	ds_read_b128 v[172:175], v155
	ds_read_b128 v[176:179], v155 offset:1024
	ds_read_b128 v[180:183], v155 offset:2048
	ds_read_b128 v[184:187], v155 offset:3072
	s_add_u32 s18, s64, 0x4000
	s_addc_u32 s19, s65, 0
	s_mov_b32 m0, s43
	ds_read_b128 v[192:195], v154 offset:32768
	ds_read_b128 v[200:203], v154 offset:33792
	ds_read_b128 v[204:207], v154 offset:34816
	ds_read_b128 v[208:211], v154 offset:35840
	ds_read_b128 v[212:215], v154 offset:36864
	ds_read_b128 v[216:219], v154 offset:37888
	ds_read_b128 v[220:223], v154 offset:38912
	ds_read_b128 v[224:227], v154 offset:39936
	global_load_lds_dwordx4 v130, s[18:19] sc1
	s_mov_b32 m0, s44
	s_nop 0
	global_load_lds_dwordx4 v128, s[18:19] sc1
	s_waitcnt vmcnt(8)
	s_waitcnt lgkmcnt(0)
	s_barrier
	s_setprio 1
	s_waitcnt lgkmcnt(0)
	v_mfma_f32_16x16x32_bf16 v[116:119], v[156:159], v[192:195], v[116:119]
	v_mfma_f32_16x16x32_bf16 v[108:111], v[164:167], v[192:195], v[108:111]
	v_mfma_f32_16x16x32_bf16 v[100:103], v[156:159], v[204:207], v[100:103]
	v_mfma_f32_16x16x32_bf16 v[92:95], v[164:167], v[204:207], v[92:95]
	v_mfma_f32_16x16x32_bf16 v[84:87], v[156:159], v[212:215], v[84:87]
	v_mfma_f32_16x16x32_bf16 v[76:79], v[164:167], v[212:215], v[76:79]
	v_mfma_f32_16x16x32_bf16 v[60:63], v[156:159], v[220:223], v[60:63]
	v_mfma_f32_16x16x32_bf16 v[52:55], v[164:167], v[220:223], v[52:55]
	v_mfma_f32_16x16x32_bf16 v[116:119], v[160:163], v[200:203], v[116:119]
	v_mfma_f32_16x16x32_bf16 v[108:111], v[168:171], v[200:203], v[108:111]
	v_mfma_f32_16x16x32_bf16 v[100:103], v[160:163], v[208:211], v[100:103]
	v_mfma_f32_16x16x32_bf16 v[92:95], v[168:171], v[208:211], v[92:95]
	v_mfma_f32_16x16x32_bf16 v[84:87], v[160:163], v[216:219], v[84:87]
	v_mfma_f32_16x16x32_bf16 v[76:79], v[168:171], v[216:219], v[76:79]
	v_mfma_f32_16x16x32_bf16 v[60:63], v[160:163], v[224:227], v[60:63]
	v_mfma_f32_16x16x32_bf16 v[52:55], v[168:171], v[224:227], v[52:55]
	s_setprio 0
	s_setprio 1
	v_mfma_f32_16x16x32_bf16 v[124:127], v[172:175], v[192:195], v[124:127]
	v_mfma_f32_16x16x32_bf16 v[120:123], v[180:183], v[192:195], v[120:123]
	v_mfma_f32_16x16x32_bf16 v[112:115], v[172:175], v[204:207], v[112:115]
	v_mfma_f32_16x16x32_bf16 v[104:107], v[180:183], v[204:207], v[104:107]
	v_mfma_f32_16x16x32_bf16 v[96:99], v[172:175], v[212:215], v[96:99]
	v_mfma_f32_16x16x32_bf16 v[88:91], v[180:183], v[212:215], v[88:91]
	v_mfma_f32_16x16x32_bf16 v[80:83], v[172:175], v[220:223], v[80:83]
	v_mfma_f32_16x16x32_bf16 v[68:71], v[180:183], v[220:223], v[68:71]
	v_mfma_f32_16x16x32_bf16 v[124:127], v[176:179], v[200:203], v[124:127]
	v_mfma_f32_16x16x32_bf16 v[120:123], v[184:187], v[200:203], v[120:123]
	v_mfma_f32_16x16x32_bf16 v[112:115], v[176:179], v[208:211], v[112:115]
	v_mfma_f32_16x16x32_bf16 v[104:107], v[184:187], v[208:211], v[104:107]
	v_mfma_f32_16x16x32_bf16 v[96:99], v[176:179], v[216:219], v[96:99]
	v_mfma_f32_16x16x32_bf16 v[88:91], v[184:187], v[216:219], v[88:91]
	v_mfma_f32_16x16x32_bf16 v[80:83], v[176:179], v[224:227], v[80:83]
	v_mfma_f32_16x16x32_bf16 v[68:71], v[184:187], v[224:227], v[68:71]
	s_setprio 0
	s_barrier
	s_add_u32 s18, s62, 0x8000
	s_addc_u32 s19, s63, 0
	s_add_i32 s64, s49, s36
	s_mov_b32 m0, s64
	ds_read_b128 v[192:195], v154 offset:49152
	ds_read_b128 v[200:203], v154 offset:50176
	ds_read_b128 v[204:207], v154 offset:51200
	ds_read_b128 v[208:211], v154 offset:52224
	ds_read_b128 v[212:215], v154 offset:53248
	ds_read_b128 v[216:219], v154 offset:54272
	ds_read_b128 v[220:223], v154 offset:55296
	ds_read_b128 v[224:227], v154 offset:56320
	global_load_lds_dwordx4 v132, s[18:19] sc1
	s_add_i32 m0, s64, 0x2000
	s_nop 0
	global_load_lds_dwordx4 v134, s[18:19] sc1
	s_add_u32 s18, s62, 0xc000
	s_addc_u32 s19, s63, 0
	s_add_i32 s62, s50, s36
	s_mov_b32 m0, s62
	s_nop 0
	global_load_lds_dwordx4 v132, s[18:19] sc1
	s_add_i32 m0, s62, 0x2000
	s_nop 0
	global_load_lds_dwordx4 v134, s[18:19] sc1
	s_mov_b32 m0, s7
	s_nop 0
	global_load_lds_dwordx4 v130, s[56:57] sc1
	s_mov_b32 m0, s45
	s_nop 0
	global_load_lds_dwordx4 v128, s[56:57] sc1
	s_waitcnt vmcnt(8)
	s_waitcnt lgkmcnt(0)
	s_barrier
	s_setprio 1
	s_waitcnt lgkmcnt(0)
	v_mfma_f32_16x16x32_bf16 v[56:59], v[156:159], v[192:195], v[56:59]
	v_mfma_f32_16x16x32_bf16 v[44:47], v[164:167], v[192:195], v[44:47]
	v_mfma_f32_16x16x32_bf16 v[36:39], v[156:159], v[204:207], v[36:39]
	v_mfma_f32_16x16x32_bf16 v[28:31], v[164:167], v[204:207], v[28:31]
	v_mfma_f32_16x16x32_bf16 v[20:23], v[156:159], v[212:215], v[20:23]
	v_mfma_f32_16x16x32_bf16 v[12:15], v[164:167], v[212:215], v[12:15]
	v_mfma_f32_16x16x32_bf16 v[4:7], v[156:159], v[220:223], v[4:7]
	v_mfma_f32_16x16x32_bf16 v[0:3], v[164:167], v[220:223], v[0:3]
	v_mfma_f32_16x16x32_bf16 v[56:59], v[160:163], v[200:203], v[56:59]
	v_mfma_f32_16x16x32_bf16 v[44:47], v[168:171], v[200:203], v[44:47]
	v_mfma_f32_16x16x32_bf16 v[36:39], v[160:163], v[208:211], v[36:39]
	v_mfma_f32_16x16x32_bf16 v[28:31], v[168:171], v[208:211], v[28:31]
	v_mfma_f32_16x16x32_bf16 v[20:23], v[160:163], v[216:219], v[20:23]
	v_mfma_f32_16x16x32_bf16 v[12:15], v[168:171], v[216:219], v[12:15]
	v_mfma_f32_16x16x32_bf16 v[4:7], v[160:163], v[224:227], v[4:7]
	v_mfma_f32_16x16x32_bf16 v[0:3], v[168:171], v[224:227], v[0:3]
	s_setprio 0
	s_setprio 1
	v_mfma_f32_16x16x32_bf16 v[72:75], v[172:175], v[192:195], v[72:75]
	v_mfma_f32_16x16x32_bf16 v[64:67], v[180:183], v[192:195], v[64:67]
	v_mfma_f32_16x16x32_bf16 v[48:51], v[172:175], v[204:207], v[48:51]
	v_mfma_f32_16x16x32_bf16 v[40:43], v[180:183], v[204:207], v[40:43]
	v_mfma_f32_16x16x32_bf16 v[32:35], v[172:175], v[212:215], v[32:35]
	v_mfma_f32_16x16x32_bf16 v[24:27], v[180:183], v[212:215], v[24:27]
	v_mfma_f32_16x16x32_bf16 v[16:19], v[172:175], v[220:223], v[16:19]
	v_mfma_f32_16x16x32_bf16 v[8:11], v[180:183], v[220:223], v[8:11]
	v_mfma_f32_16x16x32_bf16 v[72:75], v[176:179], v[200:203], v[72:75]
	v_mfma_f32_16x16x32_bf16 v[64:67], v[184:187], v[200:203], v[64:67]
	v_mfma_f32_16x16x32_bf16 v[48:51], v[176:179], v[208:211], v[48:51]
	v_mfma_f32_16x16x32_bf16 v[40:43], v[184:187], v[208:211], v[40:43]
	v_mfma_f32_16x16x32_bf16 v[32:35], v[176:179], v[216:219], v[32:35]
	v_mfma_f32_16x16x32_bf16 v[24:27], v[184:187], v[216:219], v[24:27]
	v_mfma_f32_16x16x32_bf16 v[16:19], v[176:179], v[224:227], v[16:19]
	v_mfma_f32_16x16x32_bf16 v[8:11], v[184:187], v[224:227], v[8:11]
	s_setprio 0
	s_barrier
	s_add_i32 s78, s78, 2
	s_add_u32 s76, s76, 0x10000
	s_addc_u32 s77, s77, 0
	s_cmp_gt_u32 s78, 13
	s_mov_b64 s[18:19], s[40:41]
	s_cbranch_scc0 .LBB0_1093
	s_and_b64 vcc, exec, s[10:11]
	s_cbranch_vccz .LBB0_1096
	s_barrier

.LBB0_1249:
	s_add_u32 s11, s12, s6
	v_add_u32_e32 v160, s40, v150
	s_addc_u32 s18, s13, s7
	ds_read_b128 v[152:155], v160
	ds_read_b128 v[156:159], v160 offset:1024
	ds_read_b128 v[164:167], v160 offset:2048
	ds_read_b128 v[168:171], v160 offset:3072
	v_add_u32_e32 v160, s41, v150
	s_add_u32 s11, s11, 0x10000
	ds_read_b128 v[172:175], v160
	ds_read_b128 v[182:185], v160 offset:1024
	ds_read_b128 v[190:193], v160 offset:2048
	ds_read_b128 v[194:197], v160 offset:3072
	s_addc_u32 s18, s18, 0
	s_add_u32 s19, s49, s6
	s_addc_u32 s21, s50, s7
	s_cmp_eq_u32 s6, 0x150000
	s_cselect_b32 s22, s52, s11
	s_cselect_b32 s23, s51, s18
	s_cselect_b32 s20, s54, s19
	s_cselect_b32 s21, s53, s21
	s_add_u32 s18, s22, 0x8000
	s_addc_u32 s19, s23, 0
	s_add_i32 s11, s29, 0xc000
	v_lshl_add_u64 v[160:161], v[144:145], 0, s[6:7]
	s_mov_b32 m0, s11
	s_add_i32 s48, s29, 0xe000
	ds_read_b128 v[198:201], v151
	ds_read_b128 v[202:205], v151 offset:1024
	ds_read_b128 v[206:209], v151 offset:2048
	ds_read_b128 v[210:213], v151 offset:3072
	ds_read_b128 v[214:217], v151 offset:4096
	ds_read_b128 v[218:221], v151 offset:5120
	ds_read_b128 v[222:225], v151 offset:6144
	ds_read_b128 v[226:229], v151 offset:7168
	global_load_lds_dwordx4 v[160:161], off sc1
	v_lshl_add_u64 v[160:161], v[146:147], 0, s[6:7]
	s_mov_b32 m0, s48
	s_nop 0
	global_load_lds_dwordx4 v[160:161], off sc1
	s_waitcnt vmcnt(8)
	s_waitcnt lgkmcnt(0)
	s_barrier
	s_setprio 1
	s_waitcnt lgkmcnt(0)
	v_mfma_f32_16x16x32_bf16 v[128:131], v[152:155], v[198:201], v[128:131]
	v_mfma_f32_16x16x32_bf16 v[132:135], v[164:167], v[198:201], v[132:135]
	v_mfma_f32_16x16x32_bf16 v[112:115], v[152:155], v[206:209], v[112:115]
	v_mfma_f32_16x16x32_bf16 v[116:119], v[164:167], v[206:209], v[116:119]
	v_mfma_f32_16x16x32_bf16 v[96:99], v[152:155], v[214:217], v[96:99]
	v_mfma_f32_16x16x32_bf16 v[100:103], v[164:167], v[214:217], v[100:103]
	v_mfma_f32_16x16x32_bf16 v[72:75], v[152:155], v[222:225], v[72:75]
	v_mfma_f32_16x16x32_bf16 v[76:79], v[164:167], v[222:225], v[76:79]
	v_mfma_f32_16x16x32_bf16 v[128:131], v[156:159], v[202:205], v[128:131]
	v_mfma_f32_16x16x32_bf16 v[132:135], v[168:171], v[202:205], v[132:135]
	v_mfma_f32_16x16x32_bf16 v[112:115], v[156:159], v[210:213], v[112:115]
	v_mfma_f32_16x16x32_bf16 v[116:119], v[168:171], v[210:213], v[116:119]
	v_mfma_f32_16x16x32_bf16 v[96:99], v[156:159], v[218:221], v[96:99]
	v_mfma_f32_16x16x32_bf16 v[100:103], v[168:171], v[218:221], v[100:103]
	v_mfma_f32_16x16x32_bf16 v[72:75], v[156:159], v[226:229], v[72:75]
	v_mfma_f32_16x16x32_bf16 v[76:79], v[168:171], v[226:229], v[76:79]
	s_setprio 0
	s_setprio 1
	v_mfma_f32_16x16x32_bf16 v[136:139], v[172:175], v[198:201], v[136:139]
	v_mfma_f32_16x16x32_bf16 v[140:143], v[190:193], v[198:201], v[140:143]
	v_mfma_f32_16x16x32_bf16 v[120:123], v[172:175], v[206:209], v[120:123]
	v_mfma_f32_16x16x32_bf16 v[124:127], v[190:193], v[206:209], v[124:127]
	v_mfma_f32_16x16x32_bf16 v[104:107], v[172:175], v[214:217], v[104:107]
	v_mfma_f32_16x16x32_bf16 v[108:111], v[190:193], v[214:217], v[108:111]
	v_mfma_f32_16x16x32_bf16 v[88:91], v[172:175], v[222:225], v[88:91]
	v_mfma_f32_16x16x32_bf16 v[92:95], v[190:193], v[222:225], v[92:95]
	v_mfma_f32_16x16x32_bf16 v[136:139], v[182:185], v[202:205], v[136:139]
	v_mfma_f32_16x16x32_bf16 v[140:143], v[194:197], v[202:205], v[140:143]
	v_mfma_f32_16x16x32_bf16 v[120:123], v[182:185], v[210:213], v[120:123]
	v_mfma_f32_16x16x32_bf16 v[124:127], v[194:197], v[210:213], v[124:127]
	v_mfma_f32_16x16x32_bf16 v[104:107], v[182:185], v[218:221], v[104:107]
	v_mfma_f32_16x16x32_bf16 v[108:111], v[194:197], v[218:221], v[108:111]
	v_mfma_f32_16x16x32_bf16 v[88:91], v[182:185], v[226:229], v[88:91]
	v_mfma_f32_16x16x32_bf16 v[92:95], v[194:197], v[226:229], v[92:95]
	s_setprio 0
	s_barrier
	s_add_i32 s56, s40, s27
	s_mov_b32 m0, s56
	ds_read_b128 v[198:201], v151 offset:16384
	ds_read_b128 v[202:205], v151 offset:17408
	ds_read_b128 v[206:209], v151 offset:18432
	ds_read_b128 v[210:213], v151 offset:19456
	ds_read_b128 v[214:217], v151 offset:20480
	ds_read_b128 v[218:221], v151 offset:21504
	ds_read_b128 v[222:225], v151 offset:22528
	ds_read_b128 v[226:229], v151 offset:23552
	global_load_lds_dwordx4 v2, s[20:21] sc1
	s_add_i32 m0, s56, 0x2000
	s_add_u32 s56, s20, 0x4000
	s_addc_u32 s57, s21, 0
	s_add_i32 s58, s41, s27
	global_load_lds_dwordx4 v6, s[20:21] sc1
	s_mov_b32 m0, s58
	s_nop 0
	global_load_lds_dwordx4 v2, s[56:57] sc1
	s_add_i32 m0, s58, 0x2000
	s_nop 0
	global_load_lds_dwordx4 v6, s[56:57] sc1
	s_mov_b32 m0, s29
	s_nop 0
	global_load_lds_dwordx4 v0, s[22:23] sc1
	s_mov_b32 m0, s30
	s_nop 0
	global_load_lds_dwordx4 v4, s[22:23] sc1
	s_waitcnt vmcnt(8)
	s_waitcnt lgkmcnt(0)
	s_barrier
	s_setprio 1
	s_waitcnt lgkmcnt(0)
	v_mfma_f32_16x16x32_bf16 v[64:67], v[152:155], v[198:201], v[64:67]
	v_mfma_f32_16x16x32_bf16 v[68:71], v[164:167], v[198:201], v[68:71]
	v_mfma_f32_16x16x32_bf16 v[48:51], v[152:155], v[206:209], v[48:51]
	v_mfma_f32_16x16x32_bf16 v[52:55], v[164:167], v[206:209], v[52:55]
	v_mfma_f32_16x16x32_bf16 v[32:35], v[152:155], v[214:217], v[32:35]
	v_mfma_f32_16x16x32_bf16 v[36:39], v[164:167], v[214:217], v[36:39]
	v_mfma_f32_16x16x32_bf16 v[16:19], v[152:155], v[222:225], v[16:19]
	v_mfma_f32_16x16x32_bf16 v[20:23], v[164:167], v[222:225], v[20:23]
	v_mfma_f32_16x16x32_bf16 v[64:67], v[156:159], v[202:205], v[64:67]
	v_mfma_f32_16x16x32_bf16 v[68:71], v[168:171], v[202:205], v[68:71]
	v_mfma_f32_16x16x32_bf16 v[48:51], v[156:159], v[210:213], v[48:51]
	v_mfma_f32_16x16x32_bf16 v[52:55], v[168:171], v[210:213], v[52:55]
	v_mfma_f32_16x16x32_bf16 v[32:35], v[156:159], v[218:221], v[32:35]
	v_mfma_f32_16x16x32_bf16 v[36:39], v[168:171], v[218:221], v[36:39]
	v_mfma_f32_16x16x32_bf16 v[16:19], v[156:159], v[226:229], v[16:19]
	v_mfma_f32_16x16x32_bf16 v[20:23], v[168:171], v[226:229], v[20:23]
	s_setprio 0
	s_setprio 1
	v_mfma_f32_16x16x32_bf16 v[80:83], v[172:175], v[198:201], v[80:83]
	v_mfma_f32_16x16x32_bf16 v[84:87], v[190:193], v[198:201], v[84:87]
	v_mfma_f32_16x16x32_bf16 v[56:59], v[172:175], v[206:209], v[56:59]
	v_mfma_f32_16x16x32_bf16 v[60:63], v[190:193], v[206:209], v[60:63]
	v_mfma_f32_16x16x32_bf16 v[40:43], v[172:175], v[214:217], v[40:43]
	v_mfma_f32_16x16x32_bf16 v[44:47], v[190:193], v[214:217], v[44:47]
	v_mfma_f32_16x16x32_bf16 v[24:27], v[172:175], v[222:225], v[24:27]
	v_mfma_f32_16x16x32_bf16 v[28:31], v[190:193], v[222:225], v[28:31]
	v_mfma_f32_16x16x32_bf16 v[80:83], v[182:185], v[202:205], v[80:83]
	v_mfma_f32_16x16x32_bf16 v[84:87], v[194:197], v[202:205], v[84:87]
	v_mfma_f32_16x16x32_bf16 v[56:59], v[182:185], v[210:213], v[56:59]
	v_mfma_f32_16x16x32_bf16 v[60:63], v[194:197], v[210:213], v[60:63]
	v_mfma_f32_16x16x32_bf16 v[40:43], v[182:185], v[218:221], v[40:43]
	v_mfma_f32_16x16x32_bf16 v[44:47], v[194:197], v[218:221], v[44:47]
	v_mfma_f32_16x16x32_bf16 v[24:27], v[182:185], v[226:229], v[24:27]
	v_mfma_f32_16x16x32_bf16 v[28:31], v[194:197], v[226:229], v[28:31]
	s_setprio 0
	s_barrier
	v_add_u32_e32 v160, s43, v150
	ds_read_b128 v[152:155], v160
	ds_read_b128 v[156:159], v160 offset:1024
	ds_read_b128 v[164:167], v160 offset:2048
	ds_read_b128 v[168:171], v160 offset:3072
	v_add_u32_e32 v160, s44, v150
	ds_read_b128 v[172:175], v160
	ds_read_b128 v[182:185], v160 offset:1024
	ds_read_b128 v[190:193], v160 offset:2048
	ds_read_b128 v[194:197], v160 offset:3072
	s_add_u32 s22, s22, 0x4000
	s_addc_u32 s23, s23, 0
	s_mov_b32 m0, s31
	ds_read_b128 v[198:201], v151 offset:32768
	ds_read_b128 v[202:205], v151 offset:33792
	ds_read_b128 v[206:209], v151 offset:34816
	ds_read_b128 v[210:213], v151 offset:35840
	ds_read_b128 v[214:217], v151 offset:36864
	ds_read_b128 v[218:221], v151 offset:37888
	ds_read_b128 v[222:225], v151 offset:38912
	ds_read_b128 v[226:229], v151 offset:39936
	global_load_lds_dwordx4 v0, s[22:23] sc1
	s_mov_b32 m0, s35
	s_nop 0
	global_load_lds_dwordx4 v4, s[22:23] sc1
	s_waitcnt vmcnt(8)
	s_waitcnt lgkmcnt(0)
	s_barrier
	s_setprio 1
	s_waitcnt lgkmcnt(0)
	v_mfma_f32_16x16x32_bf16 v[128:131], v[152:155], v[198:201], v[128:131]
	v_mfma_f32_16x16x32_bf16 v[132:135], v[164:167], v[198:201], v[132:135]
	v_mfma_f32_16x16x32_bf16 v[112:115], v[152:155], v[206:209], v[112:115]
	v_mfma_f32_16x16x32_bf16 v[116:119], v[164:167], v[206:209], v[116:119]
	v_mfma_f32_16x16x32_bf16 v[96:99], v[152:155], v[214:217], v[96:99]
	v_mfma_f32_16x16x32_bf16 v[100:103], v[164:167], v[214:217], v[100:103]
	v_mfma_f32_16x16x32_bf16 v[72:75], v[152:155], v[222:225], v[72:75]
	v_mfma_f32_16x16x32_bf16 v[76:79], v[164:167], v[222:225], v[76:79]
	v_mfma_f32_16x16x32_bf16 v[128:131], v[156:159], v[202:205], v[128:131]
	v_mfma_f32_16x16x32_bf16 v[132:135], v[168:171], v[202:205], v[132:135]
	v_mfma_f32_16x16x32_bf16 v[112:115], v[156:159], v[210:213], v[112:115]
	v_mfma_f32_16x16x32_bf16 v[116:119], v[168:171], v[210:213], v[116:119]
	v_mfma_f32_16x16x32_bf16 v[96:99], v[156:159], v[218:221], v[96:99]
	v_mfma_f32_16x16x32_bf16 v[100:103], v[168:171], v[218:221], v[100:103]
	v_mfma_f32_16x16x32_bf16 v[72:75], v[156:159], v[226:229], v[72:75]
	v_mfma_f32_16x16x32_bf16 v[76:79], v[168:171], v[226:229], v[76:79]
	s_setprio 0
	s_setprio 1
	v_mfma_f32_16x16x32_bf16 v[136:139], v[172:175], v[198:201], v[136:139]
	v_mfma_f32_16x16x32_bf16 v[140:143], v[190:193], v[198:201], v[140:143]
	v_mfma_f32_16x16x32_bf16 v[120:123], v[172:175], v[206:209], v[120:123]
	v_mfma_f32_16x16x32_bf16 v[124:127], v[190:193], v[206:209], v[124:127]
	v_mfma_f32_16x16x32_bf16 v[104:107], v[172:175], v[214:217], v[104:107]
	v_mfma_f32_16x16x32_bf16 v[108:111], v[190:193], v[214:217], v[108:111]
	v_mfma_f32_16x16x32_bf16 v[88:91], v[172:175], v[222:225], v[88:91]
	v_mfma_f32_16x16x32_bf16 v[92:95], v[190:193], v[222:225], v[92:95]
	v_mfma_f32_16x16x32_bf16 v[136:139], v[182:185], v[202:205], v[136:139]
	v_mfma_f32_16x16x32_bf16 v[140:143], v[194:197], v[202:205], v[140:143]
	v_mfma_f32_16x16x32_bf16 v[120:123], v[182:185], v[210:213], v[120:123]
	v_mfma_f32_16x16x32_bf16 v[124:127], v[194:197], v[210:213], v[124:127]
	v_mfma_f32_16x16x32_bf16 v[104:107], v[182:185], v[218:221], v[104:107]
	v_mfma_f32_16x16x32_bf16 v[108:111], v[194:197], v[218:221], v[108:111]
	v_mfma_f32_16x16x32_bf16 v[88:91], v[182:185], v[226:229], v[88:91]
	v_mfma_f32_16x16x32_bf16 v[92:95], v[194:197], v[226:229], v[92:95]
	s_setprio 0
	s_barrier
	s_add_u32 s22, s20, 0x8000
	s_addc_u32 s23, s21, 0
	s_add_i32 s56, s43, s27
	s_mov_b32 m0, s56
	ds_read_b128 v[198:201], v151 offset:49152
	ds_read_b128 v[202:205], v151 offset:50176
	ds_read_b128 v[206:209], v151 offset:51200
	ds_read_b128 v[210:213], v151 offset:52224
	ds_read_b128 v[214:217], v151 offset:53248
	ds_read_b128 v[218:221], v151 offset:54272
	ds_read_b128 v[222:225], v151 offset:55296
	ds_read_b128 v[226:229], v151 offset:56320
	global_load_lds_dwordx4 v2, s[22:23] sc1
	s_add_i32 m0, s56, 0x2000
	s_add_u32 s20, s20, 0xc000
	global_load_lds_dwordx4 v6, s[22:23] sc1
	s_addc_u32 s21, s21, 0
	s_add_i32 s22, s44, s27
	s_mov_b32 m0, s22
	s_nop 0
	global_load_lds_dwordx4 v2, s[20:21] sc1
	s_add_i32 m0, s22, 0x2000
	s_nop 0
	global_load_lds_dwordx4 v6, s[20:21] sc1
	s_mov_b32 m0, s38
	s_nop 0
	global_load_lds_dwordx4 v0, s[18:19] sc1
	s_mov_b32 m0, s39
	s_nop 0
	global_load_lds_dwordx4 v4, s[18:19] sc1
	s_waitcnt vmcnt(8)
	s_waitcnt lgkmcnt(0)
	s_barrier
	s_setprio 1
	s_waitcnt lgkmcnt(0)
	v_mfma_f32_16x16x32_bf16 v[64:67], v[152:155], v[198:201], v[64:67]
	v_mfma_f32_16x16x32_bf16 v[68:71], v[164:167], v[198:201], v[68:71]
	v_mfma_f32_16x16x32_bf16 v[48:51], v[152:155], v[206:209], v[48:51]
	v_mfma_f32_16x16x32_bf16 v[52:55], v[164:167], v[206:209], v[52:55]
	v_mfma_f32_16x16x32_bf16 v[32:35], v[152:155], v[214:217], v[32:35]
	v_mfma_f32_16x16x32_bf16 v[36:39], v[164:167], v[214:217], v[36:39]
	v_mfma_f32_16x16x32_bf16 v[16:19], v[152:155], v[222:225], v[16:19]
	v_mfma_f32_16x16x32_bf16 v[20:23], v[164:167], v[222:225], v[20:23]
	v_mfma_f32_16x16x32_bf16 v[64:67], v[156:159], v[202:205], v[64:67]
	v_mfma_f32_16x16x32_bf16 v[68:71], v[168:171], v[202:205], v[68:71]
	v_mfma_f32_16x16x32_bf16 v[48:51], v[156:159], v[210:213], v[48:51]
	v_mfma_f32_16x16x32_bf16 v[52:55], v[168:171], v[210:213], v[52:55]
	v_mfma_f32_16x16x32_bf16 v[32:35], v[156:159], v[218:221], v[32:35]
	v_mfma_f32_16x16x32_bf16 v[36:39], v[168:171], v[218:221], v[36:39]
	v_mfma_f32_16x16x32_bf16 v[16:19], v[156:159], v[226:229], v[16:19]
	v_mfma_f32_16x16x32_bf16 v[20:23], v[168:171], v[226:229], v[20:23]
	s_setprio 0
	s_setprio 1
	v_mfma_f32_16x16x32_bf16 v[80:83], v[172:175], v[198:201], v[80:83]
	v_mfma_f32_16x16x32_bf16 v[84:87], v[190:193], v[198:201], v[84:87]
	v_mfma_f32_16x16x32_bf16 v[56:59], v[172:175], v[206:209], v[56:59]
	v_mfma_f32_16x16x32_bf16 v[60:63], v[190:193], v[206:209], v[60:63]
	v_mfma_f32_16x16x32_bf16 v[40:43], v[172:175], v[214:217], v[40:43]
	v_mfma_f32_16x16x32_bf16 v[44:47], v[190:193], v[214:217], v[44:47]
	v_mfma_f32_16x16x32_bf16 v[24:27], v[172:175], v[222:225], v[24:27]
	v_mfma_f32_16x16x32_bf16 v[28:31], v[190:193], v[222:225], v[28:31]
	v_mfma_f32_16x16x32_bf16 v[80:83], v[182:185], v[202:205], v[80:83]
	v_mfma_f32_16x16x32_bf16 v[84:87], v[194:197], v[202:205], v[84:87]
	v_mfma_f32_16x16x32_bf16 v[56:59], v[182:185], v[210:213], v[56:59]
	v_mfma_f32_16x16x32_bf16 v[60:63], v[194:197], v[210:213], v[60:63]
	v_mfma_f32_16x16x32_bf16 v[40:43], v[182:185], v[218:221], v[40:43]
	v_mfma_f32_16x16x32_bf16 v[44:47], v[194:197], v[218:221], v[44:47]
	v_mfma_f32_16x16x32_bf16 v[24:27], v[182:185], v[226:229], v[24:27]
	v_mfma_f32_16x16x32_bf16 v[28:31], v[194:197], v[226:229], v[28:31]
	s_setprio 0
	s_barrier
	s_add_i32 s55, s55, 2
	s_add_u32 s6, s6, 0x10000
	s_addc_u32 s7, s7, 0
	s_cmp_gt_u32 s55, 41
	s_cbranch_scc0 .LBB0_1249
	s_add_u32 s6, s49, 0xffff0000
	s_addc_u32 s7, s50, -1
	s_and_b64 vcc, exec, s[4:5]
	s_cbranch_vccnz .LBB0_1236
	s_mov_b32 s8, s45
	s_mov_b32 s10, s46
	s_mov_b64 s[12:13], s[16:17]
	s_mov_b32 s42, s47
	v_mov_b64 v[128:129], 0
	v_mov_b64 v[130:131], 0
	v_mov_b64 v[132:133], 0
	v_mov_b64 v[134:135], 0
	v_mov_b64 v[112:113], 0
	v_mov_b64 v[114:115], 0
	v_mov_b64 v[116:117], 0
	v_mov_b64 v[118:119], 0
	v_mov_b64 v[96:97], 0
	v_mov_b64 v[98:99], 0
	v_mov_b64 v[100:101], 0
	v_mov_b64 v[102:103], 0
	v_mov_b64 v[72:73], 0
	v_mov_b64 v[74:75], 0
	v_mov_b64 v[76:77], 0
	v_mov_b64 v[78:79], 0
	v_mov_b64 v[136:137], 0
	v_mov_b64 v[138:139], 0
	v_mov_b64 v[140:141], 0
	v_mov_b64 v[142:143], 0
	v_mov_b64 v[120:121], 0
	v_mov_b64 v[122:123], 0
	v_mov_b64 v[124:125], 0
	v_mov_b64 v[126:127], 0
	v_mov_b64 v[104:105], 0
	v_mov_b64 v[106:107], 0
	v_mov_b64 v[108:109], 0
	v_mov_b64 v[110:111], 0
	v_mov_b64 v[88:89], 0
	v_mov_b64 v[90:91], 0
	v_mov_b64 v[92:93], 0
	v_mov_b64 v[94:95], 0
	v_mov_b64 v[64:65], 0
	v_mov_b64 v[66:67], 0
	v_mov_b64 v[68:69], 0
	v_mov_b64 v[70:71], 0
	v_mov_b64 v[48:49], 0
	v_mov_b64 v[50:51], 0
	v_mov_b64 v[52:53], 0
	v_mov_b64 v[54:55], 0
	v_mov_b64 v[32:33], 0
	v_mov_b64 v[34:35], 0
	v_mov_b64 v[36:37], 0
	v_mov_b64 v[38:39], 0
	v_mov_b64 v[16:17], 0
	v_mov_b64 v[18:19], 0
	v_mov_b64 v[20:21], 0
	v_mov_b64 v[22:23], 0
	v_mov_b64 v[80:81], 0
	v_mov_b64 v[82:83], 0
	v_mov_b64 v[84:85], 0
	v_mov_b64 v[86:87], 0
	v_mov_b64 v[56:57], 0
	v_mov_b64 v[58:59], 0
	v_mov_b64 v[60:61], 0
	v_mov_b64 v[62:63], 0
	v_mov_b64 v[40:41], 0
	v_mov_b64 v[42:43], 0
	v_mov_b64 v[44:45], 0
	v_mov_b64 v[46:47], 0
	v_mov_b64 v[24:25], 0
	v_mov_b64 v[26:27], 0
	v_mov_b64 v[28:29], 0
	v_mov_b64 v[30:31], 0
	s_andn2_b64 vcc, exec, s[0:1]
	s_cbranch_vccnz .LBB0_1237
